# single-tile GEMM phases: trailing pipeline-filler loads of the last K iteration issued with EXEC=0 (no traffic)
# speedup vs baseline: 1.0382x; 1.0014x over previous
.LBB0_450:
	ds_read_b128 v[98:101], v213
	ds_read_b128 v[102:105], v213 offset:1024
	ds_read_b128 v[106:109], v213 offset:2048
	ds_read_b128 v[110:113], v213 offset:3072
	ds_read_b128 v[146:149], v214
	ds_read_b128 v[150:153], v214 offset:1024
	ds_read_b128 v[154:157], v214 offset:2048
	ds_read_b128 v[158:161], v214 offset:3072
	s_add_u32 s34, s30, 0xfffc0080
	s_addc_u32 s35, s31, -1
	s_cmp_eq_u32 s71, 12
	s_cselect_b32 s37, s21, s35
	s_cselect_b32 s36, s27, s34
	s_cselect_b32 s35, s19, s70
	s_cselect_b32 s34, s29, s55
	s_add_i32 m0, s38, 0xc000
	ds_read_b128 v[182:185], v215
	ds_read_b128 v[186:189], v215 offset:1024
	ds_read_b128 v[190:193], v215 offset:2048
	ds_read_b128 v[194:197], v215 offset:3072
	ds_read_b128 v[198:201], v215 offset:4096
	ds_read_b128 v[202:205], v215 offset:5120
	ds_read_b128 v[206:209], v215 offset:6144
	ds_read_b128 v[218:221], v215 offset:7168
	global_load_lds_dwordx4 v174, s[30:31]
	s_add_i32 m0, s38, 0xe000
	s_nop 0
	global_load_lds_dwordx4 v176, s[30:31]
	s_waitcnt vmcnt(8)
	s_waitcnt lgkmcnt(0)
	s_barrier
	s_setprio 1
	v_mfma_f32_16x16x32_bf16 v[142:145], v[98:101], v[182:185], v[142:145]
	v_mfma_f32_16x16x32_bf16 v[138:141], v[106:109], v[182:185], v[138:141]
	v_mfma_f32_16x16x32_bf16 v[126:129], v[98:101], v[190:193], v[126:129]
	v_mfma_f32_16x16x32_bf16 v[122:125], v[106:109], v[190:193], v[122:125]
	v_mfma_f32_16x16x32_bf16 v[94:97], v[98:101], v[198:201], v[94:97]
	v_mfma_f32_16x16x32_bf16 v[90:93], v[106:109], v[198:201], v[90:93]
	v_mfma_f32_16x16x32_bf16 v[78:81], v[98:101], v[206:209], v[78:81]
	v_mfma_f32_16x16x32_bf16 v[74:77], v[106:109], v[206:209], v[74:77]
	v_mfma_f32_16x16x32_bf16 v[142:145], v[102:105], v[186:189], v[142:145]
	v_mfma_f32_16x16x32_bf16 v[138:141], v[110:113], v[186:189], v[138:141]
	v_mfma_f32_16x16x32_bf16 v[126:129], v[102:105], v[194:197], v[126:129]
	v_mfma_f32_16x16x32_bf16 v[122:125], v[110:113], v[194:197], v[122:125]
	v_mfma_f32_16x16x32_bf16 v[94:97], v[102:105], v[202:205], v[94:97]
	v_mfma_f32_16x16x32_bf16 v[90:93], v[110:113], v[202:205], v[90:93]
	v_mfma_f32_16x16x32_bf16 v[78:81], v[102:105], v[218:221], v[78:81]
	v_mfma_f32_16x16x32_bf16 v[74:77], v[110:113], v[218:221], v[74:77]
	v_mfma_f32_16x16x32_bf16 v[134:137], v[146:149], v[182:185], v[134:137]
	v_mfma_f32_16x16x32_bf16 v[130:133], v[154:157], v[182:185], v[130:133]
	v_mfma_f32_16x16x32_bf16 v[118:121], v[146:149], v[190:193], v[118:121]
	v_mfma_f32_16x16x32_bf16 v[114:117], v[154:157], v[190:193], v[114:117]
	v_mfma_f32_16x16x32_bf16 v[86:89], v[146:149], v[198:201], v[86:89]
	v_mfma_f32_16x16x32_bf16 v[82:85], v[154:157], v[198:201], v[82:85]
	v_mfma_f32_16x16x32_bf16 v[70:73], v[146:149], v[206:209], v[70:73]
	v_mfma_f32_16x16x32_bf16 v[66:69], v[154:157], v[206:209], v[66:69]
	v_mfma_f32_16x16x32_bf16 v[134:137], v[150:153], v[186:189], v[134:137]
	v_mfma_f32_16x16x32_bf16 v[130:133], v[158:161], v[186:189], v[130:133]
	v_mfma_f32_16x16x32_bf16 v[118:121], v[150:153], v[194:197], v[118:121]
	v_mfma_f32_16x16x32_bf16 v[114:117], v[158:161], v[194:197], v[114:117]
	v_mfma_f32_16x16x32_bf16 v[86:89], v[150:153], v[202:205], v[86:89]
	v_mfma_f32_16x16x32_bf16 v[82:85], v[158:161], v[202:205], v[82:85]
	v_mfma_f32_16x16x32_bf16 v[70:73], v[150:153], v[218:221], v[70:73]
	v_mfma_f32_16x16x32_bf16 v[66:69], v[158:161], v[218:221], v[66:69]
	s_setprio 0
	s_barrier
	s_add_u32 s98, s34, 0x80
	s_addc_u32 s99, s35, 0
	s_add_u32 s100, s36, 0x80
	s_addc_u32 s101, s37, 0
	s_add_i32 s74, s51, s7
	s_mov_b32 m0, s74
	ds_read_b128 v[182:185], v215 offset:16384
	ds_read_b128 v[186:189], v215 offset:17408
	ds_read_b128 v[190:193], v215 offset:18432
	ds_read_b128 v[194:197], v215 offset:19456
	ds_read_b128 v[198:201], v215 offset:20480
	ds_read_b128 v[202:205], v215 offset:21504
	ds_read_b128 v[206:209], v215 offset:22528
	ds_read_b128 v[218:221], v215 offset:23552
	s_cmp_eq_u32 s71, 12
	s_cselect_b64 exec, 0, -1
	s_cmp_lg_u32 s33, 0x100
	s_cselect_b64 exec, -1, exec
	global_load_lds_dwordx4 v164, s[34:35]
	s_add_i32 m0, s74, 0x2000
	s_add_u32 s74, s34, 0x40000
	s_addc_u32 s75, s35, 0
	s_add_i32 s76, s54, s7
	global_load_lds_dwordx4 v168, s[34:35]
	s_mov_b32 m0, s76
	s_nop 0
	global_load_lds_dwordx4 v164, s[74:75]
	s_add_i32 m0, s76, 0x2000
	s_nop 0
	global_load_lds_dwordx4 v168, s[74:75]
	s_mov_b32 m0, s38
	s_nop 0
	global_load_lds_dwordx4 v162, s[36:37]
	s_mov_b32 m0, s39
	s_nop 0
	global_load_lds_dwordx4 v166, s[36:37]
	s_mov_b64 exec, -1
	s_waitcnt vmcnt(8)
	s_waitcnt lgkmcnt(0)
	s_barrier
	s_setprio 1
	v_mfma_f32_16x16x32_bf16 v[62:65], v[98:101], v[182:185], v[62:65]
	v_mfma_f32_16x16x32_bf16 v[58:61], v[106:109], v[182:185], v[58:61]
	v_mfma_f32_16x16x32_bf16 v[46:49], v[98:101], v[190:193], v[46:49]
	v_mfma_f32_16x16x32_bf16 v[42:45], v[106:109], v[190:193], v[42:45]
	v_mfma_f32_16x16x32_bf16 v[30:33], v[98:101], v[198:201], v[30:33]
	v_mfma_f32_16x16x32_bf16 v[26:29], v[106:109], v[198:201], v[26:29]
	v_mfma_f32_16x16x32_bf16 v[14:17], v[98:101], v[206:209], v[14:17]
	v_mfma_f32_16x16x32_bf16 v[10:13], v[106:109], v[206:209], v[10:13]
	v_mfma_f32_16x16x32_bf16 v[62:65], v[102:105], v[186:189], v[62:65]
	v_mfma_f32_16x16x32_bf16 v[58:61], v[110:113], v[186:189], v[58:61]
	v_mfma_f32_16x16x32_bf16 v[46:49], v[102:105], v[194:197], v[46:49]
	v_mfma_f32_16x16x32_bf16 v[42:45], v[110:113], v[194:197], v[42:45]
	v_mfma_f32_16x16x32_bf16 v[30:33], v[102:105], v[202:205], v[30:33]
	v_mfma_f32_16x16x32_bf16 v[26:29], v[110:113], v[202:205], v[26:29]
	v_mfma_f32_16x16x32_bf16 v[14:17], v[102:105], v[218:221], v[14:17]
	v_mfma_f32_16x16x32_bf16 v[10:13], v[110:113], v[218:221], v[10:13]
	v_mfma_f32_16x16x32_bf16 v[54:57], v[146:149], v[182:185], v[54:57]
	v_mfma_f32_16x16x32_bf16 v[50:53], v[154:157], v[182:185], v[50:53]
	v_mfma_f32_16x16x32_bf16 v[38:41], v[146:149], v[190:193], v[38:41]
	v_mfma_f32_16x16x32_bf16 v[34:37], v[154:157], v[190:193], v[34:37]
	v_mfma_f32_16x16x32_bf16 v[22:25], v[146:149], v[198:201], v[22:25]
	v_mfma_f32_16x16x32_bf16 v[18:21], v[154:157], v[198:201], v[18:21]
	v_mfma_f32_16x16x32_bf16 v[6:9], v[146:149], v[206:209], v[6:9]
	v_mfma_f32_16x16x32_bf16 v[2:5], v[154:157], v[206:209], v[2:5]
	v_mfma_f32_16x16x32_bf16 v[54:57], v[150:153], v[186:189], v[54:57]
	v_mfma_f32_16x16x32_bf16 v[50:53], v[158:161], v[186:189], v[50:53]
	v_mfma_f32_16x16x32_bf16 v[38:41], v[150:153], v[194:197], v[38:41]
	v_mfma_f32_16x16x32_bf16 v[34:37], v[158:161], v[194:197], v[34:37]
	v_mfma_f32_16x16x32_bf16 v[22:25], v[150:153], v[202:205], v[22:25]
	v_mfma_f32_16x16x32_bf16 v[18:21], v[158:161], v[202:205], v[18:21]
	v_mfma_f32_16x16x32_bf16 v[6:9], v[150:153], v[218:221], v[6:9]
	v_mfma_f32_16x16x32_bf16 v[2:5], v[158:161], v[218:221], v[2:5]
	s_setprio 0
	s_barrier
	s_add_i32 s74, 0, 0x18000
	v_add_u32_e32 v1, s74, v173
	s_add_i32 s75, 0, 0x1c000
	ds_read_b128 v[98:101], v1
	ds_read_b128 v[102:105], v1 offset:1024
	ds_read_b128 v[106:109], v1 offset:2048
	ds_read_b128 v[110:113], v1 offset:3072
	v_add_u32_e32 v1, s75, v173
	ds_read_b128 v[146:149], v1
	ds_read_b128 v[150:153], v1 offset:1024
	ds_read_b128 v[154:157], v1 offset:2048
	ds_read_b128 v[158:161], v1 offset:3072
	s_add_u32 s36, s36, 0x40000
	s_addc_u32 s37, s37, 0
	s_mov_b32 m0, s40
	ds_read_b128 v[182:185], v215 offset:32768
	ds_read_b128 v[186:189], v215 offset:33792
	ds_read_b128 v[190:193], v215 offset:34816
	ds_read_b128 v[194:197], v215 offset:35840
	ds_read_b128 v[198:201], v215 offset:36864
	ds_read_b128 v[202:205], v215 offset:37888
	ds_read_b128 v[206:209], v215 offset:38912
	ds_read_b128 v[218:221], v215 offset:39936
	s_cmp_eq_u32 s71, 12
	s_cselect_b64 exec, 0, -1
	s_cmp_lg_u32 s33, 0x100
	s_cselect_b64 exec, -1, exec
	global_load_lds_dwordx4 v162, s[36:37]
	s_mov_b32 m0, s41
	s_nop 0
	global_load_lds_dwordx4 v166, s[36:37]
	s_mov_b64 exec, -1
	s_waitcnt vmcnt(8)
	s_waitcnt lgkmcnt(0)
	s_barrier
	s_setprio 1
	v_mfma_f32_16x16x32_bf16 v[142:145], v[98:101], v[182:185], v[142:145]
	v_mfma_f32_16x16x32_bf16 v[138:141], v[106:109], v[182:185], v[138:141]
	v_mfma_f32_16x16x32_bf16 v[126:129], v[98:101], v[190:193], v[126:129]
	v_mfma_f32_16x16x32_bf16 v[122:125], v[106:109], v[190:193], v[122:125]
	v_mfma_f32_16x16x32_bf16 v[94:97], v[98:101], v[198:201], v[94:97]
	v_mfma_f32_16x16x32_bf16 v[90:93], v[106:109], v[198:201], v[90:93]
	v_mfma_f32_16x16x32_bf16 v[78:81], v[98:101], v[206:209], v[78:81]
	v_mfma_f32_16x16x32_bf16 v[74:77], v[106:109], v[206:209], v[74:77]
	v_mfma_f32_16x16x32_bf16 v[142:145], v[102:105], v[186:189], v[142:145]
	v_mfma_f32_16x16x32_bf16 v[138:141], v[110:113], v[186:189], v[138:141]
	v_mfma_f32_16x16x32_bf16 v[126:129], v[102:105], v[194:197], v[126:129]
	v_mfma_f32_16x16x32_bf16 v[122:125], v[110:113], v[194:197], v[122:125]
	v_mfma_f32_16x16x32_bf16 v[94:97], v[102:105], v[202:205], v[94:97]
	v_mfma_f32_16x16x32_bf16 v[90:93], v[110:113], v[202:205], v[90:93]
	v_mfma_f32_16x16x32_bf16 v[78:81], v[102:105], v[218:221], v[78:81]
	v_mfma_f32_16x16x32_bf16 v[74:77], v[110:113], v[218:221], v[74:77]
	v_mfma_f32_16x16x32_bf16 v[134:137], v[146:149], v[182:185], v[134:137]
	v_mfma_f32_16x16x32_bf16 v[130:133], v[154:157], v[182:185], v[130:133]
	v_mfma_f32_16x16x32_bf16 v[118:121], v[146:149], v[190:193], v[118:121]
	v_mfma_f32_16x16x32_bf16 v[114:117], v[154:157], v[190:193], v[114:117]
	v_mfma_f32_16x16x32_bf16 v[86:89], v[146:149], v[198:201], v[86:89]
	v_mfma_f32_16x16x32_bf16 v[82:85], v[154:157], v[198:201], v[82:85]
	v_mfma_f32_16x16x32_bf16 v[70:73], v[146:149], v[206:209], v[70:73]
	v_mfma_f32_16x16x32_bf16 v[66:69], v[154:157], v[206:209], v[66:69]
	v_mfma_f32_16x16x32_bf16 v[134:137], v[150:153], v[186:189], v[134:137]
	v_mfma_f32_16x16x32_bf16 v[130:133], v[158:161], v[186:189], v[130:133]
	v_mfma_f32_16x16x32_bf16 v[118:121], v[150:153], v[194:197], v[118:121]
	v_mfma_f32_16x16x32_bf16 v[114:117], v[158:161], v[194:197], v[114:117]
	v_mfma_f32_16x16x32_bf16 v[86:89], v[150:153], v[202:205], v[86:89]
	v_mfma_f32_16x16x32_bf16 v[82:85], v[158:161], v[202:205], v[82:85]
	v_mfma_f32_16x16x32_bf16 v[70:73], v[150:153], v[218:221], v[70:73]
	v_mfma_f32_16x16x32_bf16 v[66:69], v[158:161], v[218:221], v[66:69]
	s_setprio 0
	s_barrier
	s_add_i32 s36, s74, s7
	s_mov_b32 m0, s36
	ds_read_b128 v[182:185], v215 offset:49152
	ds_read_b128 v[186:189], v215 offset:50176
	ds_read_b128 v[190:193], v215 offset:51200
	ds_read_b128 v[194:197], v215 offset:52224
	ds_read_b128 v[198:201], v215 offset:53248
	ds_read_b128 v[202:205], v215 offset:54272
	ds_read_b128 v[206:209], v215 offset:55296
	ds_read_b128 v[218:221], v215 offset:56320
	s_cmp_eq_u32 s71, 12
	s_cselect_b64 exec, 0, -1
	s_cmp_lg_u32 s33, 0x100
	s_cselect_b64 exec, -1, exec
	global_load_lds_dwordx4 v164, s[98:99]
	s_add_i32 m0, s36, 0x2000
	s_add_u32 s34, s34, 0x40080
	s_addc_u32 s35, s35, 0
	s_add_i32 s36, s75, s7
	global_load_lds_dwordx4 v168, s[98:99]
	s_mov_b32 m0, s36
	s_nop 0
	global_load_lds_dwordx4 v164, s[34:35]
	s_add_i32 m0, s36, 0x2000
	s_nop 0
	global_load_lds_dwordx4 v168, s[34:35]
	s_mov_b32 m0, s47
	s_nop 0
	global_load_lds_dwordx4 v162, s[100:101]
	s_mov_b32 m0, s48
	s_nop 0
	global_load_lds_dwordx4 v166, s[100:101]
	s_mov_b64 exec, -1
	s_waitcnt vmcnt(8)
	s_waitcnt lgkmcnt(0)
	s_barrier
	s_setprio 1
	v_mfma_f32_16x16x32_bf16 v[62:65], v[98:101], v[182:185], v[62:65]
	v_mfma_f32_16x16x32_bf16 v[58:61], v[106:109], v[182:185], v[58:61]
	v_mfma_f32_16x16x32_bf16 v[46:49], v[98:101], v[190:193], v[46:49]
	v_mfma_f32_16x16x32_bf16 v[42:45], v[106:109], v[190:193], v[42:45]
	v_mfma_f32_16x16x32_bf16 v[30:33], v[98:101], v[198:201], v[30:33]
	v_mfma_f32_16x16x32_bf16 v[26:29], v[106:109], v[198:201], v[26:29]
	v_mfma_f32_16x16x32_bf16 v[14:17], v[98:101], v[206:209], v[14:17]
	v_mfma_f32_16x16x32_bf16 v[10:13], v[106:109], v[206:209], v[10:13]
	v_mfma_f32_16x16x32_bf16 v[62:65], v[102:105], v[186:189], v[62:65]
	v_mfma_f32_16x16x32_bf16 v[58:61], v[110:113], v[186:189], v[58:61]
	v_mfma_f32_16x16x32_bf16 v[46:49], v[102:105], v[194:197], v[46:49]
	v_mfma_f32_16x16x32_bf16 v[42:45], v[110:113], v[194:197], v[42:45]
	v_mfma_f32_16x16x32_bf16 v[30:33], v[102:105], v[202:205], v[30:33]
	v_mfma_f32_16x16x32_bf16 v[26:29], v[110:113], v[202:205], v[26:29]
	v_mfma_f32_16x16x32_bf16 v[14:17], v[102:105], v[218:221], v[14:17]
	v_mfma_f32_16x16x32_bf16 v[10:13], v[110:113], v[218:221], v[10:13]
	v_mfma_f32_16x16x32_bf16 v[54:57], v[146:149], v[182:185], v[54:57]
	v_mfma_f32_16x16x32_bf16 v[50:53], v[154:157], v[182:185], v[50:53]
	v_mfma_f32_16x16x32_bf16 v[38:41], v[146:149], v[190:193], v[38:41]
	v_mfma_f32_16x16x32_bf16 v[34:37], v[154:157], v[190:193], v[34:37]
	v_mfma_f32_16x16x32_bf16 v[22:25], v[146:149], v[198:201], v[22:25]
	v_mfma_f32_16x16x32_bf16 v[18:21], v[154:157], v[198:201], v[18:21]
	v_mfma_f32_16x16x32_bf16 v[6:9], v[146:149], v[206:209], v[6:9]
	v_mfma_f32_16x16x32_bf16 v[2:5], v[154:157], v[206:209], v[2:5]
	v_mfma_f32_16x16x32_bf16 v[54:57], v[150:153], v[186:189], v[54:57]
	v_mfma_f32_16x16x32_bf16 v[50:53], v[158:161], v[186:189], v[50:53]
	v_mfma_f32_16x16x32_bf16 v[38:41], v[150:153], v[194:197], v[38:41]
	v_mfma_f32_16x16x32_bf16 v[34:37], v[158:161], v[194:197], v[34:37]
	v_mfma_f32_16x16x32_bf16 v[22:25], v[150:153], v[202:205], v[22:25]
	v_mfma_f32_16x16x32_bf16 v[18:21], v[158:161], v[202:205], v[18:21]
	v_mfma_f32_16x16x32_bf16 v[6:9], v[150:153], v[218:221], v[6:9]
	v_mfma_f32_16x16x32_bf16 v[2:5], v[158:161], v[218:221], v[2:5]
	s_setprio 0
	s_barrier
	s_add_i32 s71, s71, 2
	s_add_u32 s30, s30, 0x100
	s_addc_u32 s31, s31, 0
	s_add_u32 s55, s55, 0x100
	s_addc_u32 s70, s70, 0
	s_cmp_gt_u32 s71, 13
	s_cbranch_scc0 .LBB0_450
	s_and_b64 vcc, exec, s[16:17]
	s_cbranch_vccz .LBB0_453
	s_barrier

.LBB0_733:
	ds_read_b128 v[78:81], v184
	ds_read_b128 v[86:89], v184 offset:1024
	ds_read_b128 v[90:93], v184 offset:2048
	ds_read_b128 v[94:97], v184 offset:3072
	ds_read_b128 v[146:149], v185
	ds_read_b128 v[150:153], v185 offset:1024
	ds_read_b128 v[176:179], v185 offset:2048
	ds_read_b128 v[180:183], v185 offset:3072
	s_add_u32 s26, s24, 0xfff50080
	s_addc_u32 s27, s25, -1
	s_cmp_eq_u32 s51, 40
	s_cselect_b32 s29, s9, s27
	s_cselect_b32 s28, s8, s26
	s_cselect_b32 s27, s23, s50
	s_cselect_b32 s26, s22, s49
	s_add_i32 m0, s34, 0xc000
	ds_read_b128 v[188:191], v186
	ds_read_b128 v[192:195], v186 offset:1024
	ds_read_b128 v[196:199], v186 offset:2048
	ds_read_b128 v[200:203], v186 offset:3072
	ds_read_b128 v[204:207], v186 offset:4096
	ds_read_b128 v[208:211], v186 offset:5120
	ds_read_b128 v[212:215], v186 offset:6144
	ds_read_b128 v[216:219], v186 offset:7168
	global_load_lds_dwordx4 v162, s[24:25]
	s_add_i32 m0, s34, 0xe000
	s_nop 0
	global_load_lds_dwordx4 v164, s[24:25]
	s_waitcnt vmcnt(8)
	s_waitcnt lgkmcnt(0)
	s_barrier
	s_setprio 1
	v_mfma_f32_16x16x32_bf16 v[142:145], v[78:81], v[188:191], v[142:145]
	v_mfma_f32_16x16x32_bf16 v[138:141], v[90:93], v[188:191], v[138:141]
	v_mfma_f32_16x16x32_bf16 v[126:129], v[78:81], v[196:199], v[126:129]
	v_mfma_f32_16x16x32_bf16 v[122:125], v[90:93], v[196:199], v[122:125]
	v_mfma_f32_16x16x32_bf16 v[110:113], v[78:81], v[204:207], v[110:113]
	v_mfma_f32_16x16x32_bf16 v[106:109], v[90:93], v[204:207], v[106:109]
	v_mfma_f32_16x16x32_bf16 v[82:85], v[78:81], v[212:215], v[82:85]
	v_mfma_f32_16x16x32_bf16 v[74:77], v[90:93], v[212:215], v[74:77]
	v_mfma_f32_16x16x32_bf16 v[142:145], v[86:89], v[192:195], v[142:145]
	v_mfma_f32_16x16x32_bf16 v[138:141], v[94:97], v[192:195], v[138:141]
	v_mfma_f32_16x16x32_bf16 v[126:129], v[86:89], v[200:203], v[126:129]
	v_mfma_f32_16x16x32_bf16 v[122:125], v[94:97], v[200:203], v[122:125]
	v_mfma_f32_16x16x32_bf16 v[110:113], v[86:89], v[208:211], v[110:113]
	v_mfma_f32_16x16x32_bf16 v[106:109], v[94:97], v[208:211], v[106:109]
	v_mfma_f32_16x16x32_bf16 v[82:85], v[86:89], v[216:219], v[82:85]
	v_mfma_f32_16x16x32_bf16 v[74:77], v[94:97], v[216:219], v[74:77]
	v_mfma_f32_16x16x32_bf16 v[134:137], v[146:149], v[188:191], v[134:137]
	v_mfma_f32_16x16x32_bf16 v[130:133], v[176:179], v[188:191], v[130:133]
	v_mfma_f32_16x16x32_bf16 v[118:121], v[146:149], v[196:199], v[118:121]
	v_mfma_f32_16x16x32_bf16 v[114:117], v[176:179], v[196:199], v[114:117]
	v_mfma_f32_16x16x32_bf16 v[102:105], v[146:149], v[204:207], v[102:105]
	v_mfma_f32_16x16x32_bf16 v[98:101], v[176:179], v[204:207], v[98:101]
	v_mfma_f32_16x16x32_bf16 v[70:73], v[146:149], v[212:215], v[70:73]
	v_mfma_f32_16x16x32_bf16 v[66:69], v[176:179], v[212:215], v[66:69]
	v_mfma_f32_16x16x32_bf16 v[134:137], v[150:153], v[192:195], v[134:137]
	v_mfma_f32_16x16x32_bf16 v[130:133], v[180:183], v[192:195], v[130:133]
	v_mfma_f32_16x16x32_bf16 v[118:121], v[150:153], v[200:203], v[118:121]
	v_mfma_f32_16x16x32_bf16 v[114:117], v[180:183], v[200:203], v[114:117]
	v_mfma_f32_16x16x32_bf16 v[102:105], v[150:153], v[208:211], v[102:105]
	v_mfma_f32_16x16x32_bf16 v[98:101], v[180:183], v[208:211], v[98:101]
	v_mfma_f32_16x16x32_bf16 v[70:73], v[150:153], v[216:219], v[70:73]
	v_mfma_f32_16x16x32_bf16 v[66:69], v[180:183], v[216:219], v[66:69]
	s_setprio 0
	s_barrier
	s_add_u32 s98, s26, 0x80
	s_addc_u32 s99, s27, 0
	s_add_u32 s100, s28, 0x80
	s_addc_u32 s101, s29, 0
	s_add_i32 s54, s43, s31
	s_mov_b32 m0, s54
	ds_read_b128 v[188:191], v186 offset:16384
	ds_read_b128 v[192:195], v186 offset:17408
	ds_read_b128 v[196:199], v186 offset:18432
	ds_read_b128 v[200:203], v186 offset:19456
	ds_read_b128 v[204:207], v186 offset:20480
	ds_read_b128 v[208:211], v186 offset:21504
	ds_read_b128 v[212:215], v186 offset:22528
	ds_read_b128 v[216:219], v186 offset:23552
	s_cmp_eq_u32 s51, 40
	s_cselect_b64 exec, 0, -1
	s_cmp_lg_u32 s33, 0x100
	s_cselect_b64 exec, -1, exec
	global_load_lds_dwordx4 v156, s[26:27]
	s_add_i32 m0, s54, 0x2000
	s_add_u32 s54, s26, 0xb0000
	s_addc_u32 s55, s27, 0
	s_add_i32 s58, s44, s31
	global_load_lds_dwordx4 v160, s[26:27]
	s_mov_b32 m0, s58
	s_nop 0
	global_load_lds_dwordx4 v156, s[54:55]
	s_add_i32 m0, s58, 0x2000
	s_nop 0
	global_load_lds_dwordx4 v160, s[54:55]
	s_mov_b32 m0, s34
	s_nop 0
	global_load_lds_dwordx4 v154, s[28:29]
	s_mov_b32 m0, s35
	s_nop 0
	global_load_lds_dwordx4 v158, s[28:29]
	s_mov_b64 exec, -1
	s_waitcnt vmcnt(8)
	s_waitcnt lgkmcnt(0)
	s_barrier
	s_setprio 1
	v_mfma_f32_16x16x32_bf16 v[62:65], v[78:81], v[188:191], v[62:65]
	v_mfma_f32_16x16x32_bf16 v[58:61], v[90:93], v[188:191], v[58:61]
	v_mfma_f32_16x16x32_bf16 v[46:49], v[78:81], v[196:199], v[46:49]
	v_mfma_f32_16x16x32_bf16 v[42:45], v[90:93], v[196:199], v[42:45]
	v_mfma_f32_16x16x32_bf16 v[30:33], v[78:81], v[204:207], v[30:33]
	v_mfma_f32_16x16x32_bf16 v[26:29], v[90:93], v[204:207], v[26:29]
	v_mfma_f32_16x16x32_bf16 v[14:17], v[78:81], v[212:215], v[14:17]
	v_mfma_f32_16x16x32_bf16 v[10:13], v[90:93], v[212:215], v[10:13]
	v_mfma_f32_16x16x32_bf16 v[62:65], v[86:89], v[192:195], v[62:65]
	v_mfma_f32_16x16x32_bf16 v[58:61], v[94:97], v[192:195], v[58:61]
	v_mfma_f32_16x16x32_bf16 v[46:49], v[86:89], v[200:203], v[46:49]
	v_mfma_f32_16x16x32_bf16 v[42:45], v[94:97], v[200:203], v[42:45]
	v_mfma_f32_16x16x32_bf16 v[30:33], v[86:89], v[208:211], v[30:33]
	v_mfma_f32_16x16x32_bf16 v[26:29], v[94:97], v[208:211], v[26:29]
	v_mfma_f32_16x16x32_bf16 v[14:17], v[86:89], v[216:219], v[14:17]
	v_mfma_f32_16x16x32_bf16 v[10:13], v[94:97], v[216:219], v[10:13]
	v_mfma_f32_16x16x32_bf16 v[54:57], v[146:149], v[188:191], v[54:57]
	v_mfma_f32_16x16x32_bf16 v[50:53], v[176:179], v[188:191], v[50:53]
	v_mfma_f32_16x16x32_bf16 v[38:41], v[146:149], v[196:199], v[38:41]
	v_mfma_f32_16x16x32_bf16 v[34:37], v[176:179], v[196:199], v[34:37]
	v_mfma_f32_16x16x32_bf16 v[22:25], v[146:149], v[204:207], v[22:25]
	v_mfma_f32_16x16x32_bf16 v[18:21], v[176:179], v[204:207], v[18:21]
	v_mfma_f32_16x16x32_bf16 v[6:9], v[146:149], v[212:215], v[6:9]
	v_mfma_f32_16x16x32_bf16 v[2:5], v[176:179], v[212:215], v[2:5]
	v_mfma_f32_16x16x32_bf16 v[54:57], v[150:153], v[192:195], v[54:57]
	v_mfma_f32_16x16x32_bf16 v[50:53], v[180:183], v[192:195], v[50:53]
	v_mfma_f32_16x16x32_bf16 v[38:41], v[150:153], v[200:203], v[38:41]
	v_mfma_f32_16x16x32_bf16 v[34:37], v[180:183], v[200:203], v[34:37]
	v_mfma_f32_16x16x32_bf16 v[22:25], v[150:153], v[208:211], v[22:25]
	v_mfma_f32_16x16x32_bf16 v[18:21], v[180:183], v[208:211], v[18:21]
	v_mfma_f32_16x16x32_bf16 v[6:9], v[150:153], v[216:219], v[6:9]
	v_mfma_f32_16x16x32_bf16 v[2:5], v[180:183], v[216:219], v[2:5]
	s_setprio 0
	s_barrier
	s_add_i32 s54, 0, 0x18000
	v_add_u32_e32 v1, s54, v173
	s_add_i32 s55, 0, 0x1c000
	ds_read_b128 v[78:81], v1
	ds_read_b128 v[86:89], v1 offset:1024
	ds_read_b128 v[90:93], v1 offset:2048
	ds_read_b128 v[94:97], v1 offset:3072
	v_add_u32_e32 v1, s55, v173
	ds_read_b128 v[146:149], v1
	ds_read_b128 v[150:153], v1 offset:1024
	ds_read_b128 v[176:179], v1 offset:2048
	ds_read_b128 v[180:183], v1 offset:3072
	s_add_u32 s28, s28, 0xb0000
	s_addc_u32 s29, s29, 0
	s_mov_b32 m0, s36
	ds_read_b128 v[188:191], v186 offset:32768
	ds_read_b128 v[192:195], v186 offset:33792
	ds_read_b128 v[196:199], v186 offset:34816
	ds_read_b128 v[200:203], v186 offset:35840
	ds_read_b128 v[204:207], v186 offset:36864
	ds_read_b128 v[208:211], v186 offset:37888
	ds_read_b128 v[212:215], v186 offset:38912
	ds_read_b128 v[216:219], v186 offset:39936
	s_cmp_eq_u32 s51, 40
	s_cselect_b64 exec, 0, -1
	s_cmp_lg_u32 s33, 0x100
	s_cselect_b64 exec, -1, exec
	global_load_lds_dwordx4 v154, s[28:29]
	s_mov_b32 m0, s37
	s_nop 0
	global_load_lds_dwordx4 v158, s[28:29]
	s_mov_b64 exec, -1
	s_waitcnt vmcnt(8)
	s_waitcnt lgkmcnt(0)
	s_barrier
	s_setprio 1
	v_mfma_f32_16x16x32_bf16 v[142:145], v[78:81], v[188:191], v[142:145]
	v_mfma_f32_16x16x32_bf16 v[138:141], v[90:93], v[188:191], v[138:141]
	v_mfma_f32_16x16x32_bf16 v[126:129], v[78:81], v[196:199], v[126:129]
	v_mfma_f32_16x16x32_bf16 v[122:125], v[90:93], v[196:199], v[122:125]
	v_mfma_f32_16x16x32_bf16 v[110:113], v[78:81], v[204:207], v[110:113]
	v_mfma_f32_16x16x32_bf16 v[106:109], v[90:93], v[204:207], v[106:109]
	v_mfma_f32_16x16x32_bf16 v[82:85], v[78:81], v[212:215], v[82:85]
	v_mfma_f32_16x16x32_bf16 v[74:77], v[90:93], v[212:215], v[74:77]
	v_mfma_f32_16x16x32_bf16 v[142:145], v[86:89], v[192:195], v[142:145]
	v_mfma_f32_16x16x32_bf16 v[138:141], v[94:97], v[192:195], v[138:141]
	v_mfma_f32_16x16x32_bf16 v[126:129], v[86:89], v[200:203], v[126:129]
	v_mfma_f32_16x16x32_bf16 v[122:125], v[94:97], v[200:203], v[122:125]
	v_mfma_f32_16x16x32_bf16 v[110:113], v[86:89], v[208:211], v[110:113]
	v_mfma_f32_16x16x32_bf16 v[106:109], v[94:97], v[208:211], v[106:109]
	v_mfma_f32_16x16x32_bf16 v[82:85], v[86:89], v[216:219], v[82:85]
	v_mfma_f32_16x16x32_bf16 v[74:77], v[94:97], v[216:219], v[74:77]
	v_mfma_f32_16x16x32_bf16 v[134:137], v[146:149], v[188:191], v[134:137]
	v_mfma_f32_16x16x32_bf16 v[130:133], v[176:179], v[188:191], v[130:133]
	v_mfma_f32_16x16x32_bf16 v[118:121], v[146:149], v[196:199], v[118:121]
	v_mfma_f32_16x16x32_bf16 v[114:117], v[176:179], v[196:199], v[114:117]
	v_mfma_f32_16x16x32_bf16 v[102:105], v[146:149], v[204:207], v[102:105]
	v_mfma_f32_16x16x32_bf16 v[98:101], v[176:179], v[204:207], v[98:101]
	v_mfma_f32_16x16x32_bf16 v[70:73], v[146:149], v[212:215], v[70:73]
	v_mfma_f32_16x16x32_bf16 v[66:69], v[176:179], v[212:215], v[66:69]
	v_mfma_f32_16x16x32_bf16 v[134:137], v[150:153], v[192:195], v[134:137]
	v_mfma_f32_16x16x32_bf16 v[130:133], v[180:183], v[192:195], v[130:133]
	v_mfma_f32_16x16x32_bf16 v[118:121], v[150:153], v[200:203], v[118:121]
	v_mfma_f32_16x16x32_bf16 v[114:117], v[180:183], v[200:203], v[114:117]
	v_mfma_f32_16x16x32_bf16 v[102:105], v[150:153], v[208:211], v[102:105]
	v_mfma_f32_16x16x32_bf16 v[98:101], v[180:183], v[208:211], v[98:101]
	v_mfma_f32_16x16x32_bf16 v[70:73], v[150:153], v[216:219], v[70:73]
	v_mfma_f32_16x16x32_bf16 v[66:69], v[180:183], v[216:219], v[66:69]
	s_setprio 0
	s_barrier
	s_add_i32 s28, s54, s31
	s_mov_b32 m0, s28
	ds_read_b128 v[188:191], v186 offset:49152
	ds_read_b128 v[192:195], v186 offset:50176
	ds_read_b128 v[196:199], v186 offset:51200
	ds_read_b128 v[200:203], v186 offset:52224
	ds_read_b128 v[204:207], v186 offset:53248
	ds_read_b128 v[208:211], v186 offset:54272
	ds_read_b128 v[212:215], v186 offset:55296
	ds_read_b128 v[216:219], v186 offset:56320
	s_cmp_eq_u32 s51, 40
	s_cselect_b64 exec, 0, -1
	s_cmp_lg_u32 s33, 0x100
	s_cselect_b64 exec, -1, exec
	global_load_lds_dwordx4 v156, s[98:99]
	s_add_i32 m0, s28, 0x2000
	s_add_u32 s26, s26, 0xb0080
	s_addc_u32 s27, s27, 0
	s_add_i32 s28, s55, s31
	global_load_lds_dwordx4 v160, s[98:99]
	s_mov_b32 m0, s28
	s_nop 0
	global_load_lds_dwordx4 v156, s[26:27]
	s_add_i32 m0, s28, 0x2000
	s_nop 0
	global_load_lds_dwordx4 v160, s[26:27]
	s_mov_b32 m0, s41
	s_nop 0
	global_load_lds_dwordx4 v154, s[100:101]
	s_mov_b32 m0, s42
	s_nop 0
	global_load_lds_dwordx4 v158, s[100:101]
	s_mov_b64 exec, -1
	s_waitcnt vmcnt(8)
	s_waitcnt lgkmcnt(0)
	s_barrier
	s_setprio 1
	v_mfma_f32_16x16x32_bf16 v[62:65], v[78:81], v[188:191], v[62:65]
	v_mfma_f32_16x16x32_bf16 v[58:61], v[90:93], v[188:191], v[58:61]
	v_mfma_f32_16x16x32_bf16 v[46:49], v[78:81], v[196:199], v[46:49]
	v_mfma_f32_16x16x32_bf16 v[42:45], v[90:93], v[196:199], v[42:45]
	v_mfma_f32_16x16x32_bf16 v[30:33], v[78:81], v[204:207], v[30:33]
	v_mfma_f32_16x16x32_bf16 v[26:29], v[90:93], v[204:207], v[26:29]
	v_mfma_f32_16x16x32_bf16 v[14:17], v[78:81], v[212:215], v[14:17]
	v_mfma_f32_16x16x32_bf16 v[10:13], v[90:93], v[212:215], v[10:13]
	v_mfma_f32_16x16x32_bf16 v[62:65], v[86:89], v[192:195], v[62:65]
	v_mfma_f32_16x16x32_bf16 v[58:61], v[94:97], v[192:195], v[58:61]
	v_mfma_f32_16x16x32_bf16 v[46:49], v[86:89], v[200:203], v[46:49]
	v_mfma_f32_16x16x32_bf16 v[42:45], v[94:97], v[200:203], v[42:45]
	v_mfma_f32_16x16x32_bf16 v[30:33], v[86:89], v[208:211], v[30:33]
	v_mfma_f32_16x16x32_bf16 v[26:29], v[94:97], v[208:211], v[26:29]
	v_mfma_f32_16x16x32_bf16 v[14:17], v[86:89], v[216:219], v[14:17]
	v_mfma_f32_16x16x32_bf16 v[10:13], v[94:97], v[216:219], v[10:13]
	v_mfma_f32_16x16x32_bf16 v[54:57], v[146:149], v[188:191], v[54:57]
	v_mfma_f32_16x16x32_bf16 v[50:53], v[176:179], v[188:191], v[50:53]
	v_mfma_f32_16x16x32_bf16 v[38:41], v[146:149], v[196:199], v[38:41]
	v_mfma_f32_16x16x32_bf16 v[34:37], v[176:179], v[196:199], v[34:37]
	v_mfma_f32_16x16x32_bf16 v[22:25], v[146:149], v[204:207], v[22:25]
	v_mfma_f32_16x16x32_bf16 v[18:21], v[176:179], v[204:207], v[18:21]
	v_mfma_f32_16x16x32_bf16 v[6:9], v[146:149], v[212:215], v[6:9]
	v_mfma_f32_16x16x32_bf16 v[2:5], v[176:179], v[212:215], v[2:5]
	v_mfma_f32_16x16x32_bf16 v[54:57], v[150:153], v[192:195], v[54:57]
	v_mfma_f32_16x16x32_bf16 v[50:53], v[180:183], v[192:195], v[50:53]
	v_mfma_f32_16x16x32_bf16 v[38:41], v[150:153], v[200:203], v[38:41]
	v_mfma_f32_16x16x32_bf16 v[34:37], v[180:183], v[200:203], v[34:37]
	v_mfma_f32_16x16x32_bf16 v[22:25], v[150:153], v[208:211], v[22:25]
	v_mfma_f32_16x16x32_bf16 v[18:21], v[180:183], v[208:211], v[18:21]
	v_mfma_f32_16x16x32_bf16 v[6:9], v[150:153], v[216:219], v[6:9]
	v_mfma_f32_16x16x32_bf16 v[2:5], v[180:183], v[216:219], v[2:5]
	s_setprio 0
	s_barrier
	s_add_i32 s51, s51, 2
	s_add_u32 s24, s24, 0x100
	s_addc_u32 s25, s25, 0
	s_add_u32 s49, s49, 0x100
	s_addc_u32 s50, s50, 0
	s_cmp_gt_u32 s51, 41
	s_cbranch_scc0 .LBB0_733
	s_and_b64 vcc, exec, s[20:21]
	s_cbranch_vccz .LBB0_736
	s_barrier

.LBB0_1203:
	s_ashr_i32 s35, s34, 31
	s_lshl_b64 s[36:37], s[34:35], 19
	ds_read_b128 v[2:5], v190
	ds_read_b128 v[6:9], v190 offset:1024
	ds_read_b128 v[10:13], v190 offset:2048
	ds_read_b128 v[14:17], v190 offset:3072
	ds_read_b128 v[18:21], v191
	ds_read_b128 v[22:25], v191 offset:1024
	ds_read_b128 v[26:29], v191 offset:2048
	ds_read_b128 v[30:33], v191 offset:3072
	s_add_u32 s9, s52, s36
	s_addc_u32 s35, s53, s37
	s_ashr_i32 s31, s30, 31
	s_lshl_b64 s[36:37], s[30:31], 9
	s_add_u32 s36, s9, s36
	s_addc_u32 s37, s35, s37
	s_and_b64 s[38:39], s[4:5], exec
	s_cselect_b32 s49, s37, s41
	s_cselect_b32 s48, s36, s40
	s_lshl_b64 s[38:39], s[30:31], 17
	s_add_u32 s38, s3, s38
	s_addc_u32 s39, s6, s39
	s_and_b64 s[46:47], s[4:5], exec
	s_cselect_b32 s47, s39, s45
	s_cselect_b32 s46, s38, s44
	s_add_u32 s74, s40, 0x40080
	s_addc_u32 s75, s41, 0
	s_add_i32 s77, s43, 0xc000
	v_lshl_add_u64 v[66:67], s[74:75], 0, v[146:147]
	s_mov_b32 m0, s77
	s_add_i32 s9, s43, 0xe000
	ds_read_b128 v[34:37], v192
	ds_read_b128 v[38:41], v192 offset:1024
	ds_read_b128 v[42:45], v192 offset:2048
	ds_read_b128 v[46:49], v192 offset:3072
	ds_read_b128 v[50:53], v192 offset:4096
	ds_read_b128 v[54:57], v192 offset:5120
	ds_read_b128 v[58:61], v192 offset:6144
	ds_read_b128 v[62:65], v192 offset:7168
	global_load_lds_dwordx4 v[66:67], off
	v_lshl_add_u64 v[66:67], s[74:75], 0, v[150:151]
	s_mov_b32 m0, s9
	s_nop 0
	global_load_lds_dwordx4 v[66:67], off
	s_waitcnt vmcnt(8)
	s_waitcnt lgkmcnt(0)
	s_barrier
	s_setprio 1
	v_mfma_f32_16x16x32_bf16 v[66:69], v[2:5], v[34:37], 0
	v_mfma_f32_16x16x32_bf16 v[70:73], v[10:13], v[34:37], 0
	v_mfma_f32_16x16x32_bf16 v[74:77], v[2:5], v[42:45], 0
	v_mfma_f32_16x16x32_bf16 v[78:81], v[10:13], v[42:45], 0
	v_mfma_f32_16x16x32_bf16 v[82:85], v[2:5], v[50:53], 0
	v_mfma_f32_16x16x32_bf16 v[86:89], v[10:13], v[50:53], 0
	v_mfma_f32_16x16x32_bf16 v[90:93], v[2:5], v[58:61], 0
	v_mfma_f32_16x16x32_bf16 v[94:97], v[10:13], v[58:61], 0
	v_mfma_f32_16x16x32_bf16 v[66:69], v[6:9], v[38:41], v[66:69]
	v_mfma_f32_16x16x32_bf16 v[70:73], v[14:17], v[38:41], v[70:73]
	v_mfma_f32_16x16x32_bf16 v[74:77], v[6:9], v[46:49], v[74:77]
	v_mfma_f32_16x16x32_bf16 v[78:81], v[14:17], v[46:49], v[78:81]
	v_mfma_f32_16x16x32_bf16 v[82:85], v[6:9], v[54:57], v[82:85]
	v_mfma_f32_16x16x32_bf16 v[86:89], v[14:17], v[54:57], v[86:89]
	v_mfma_f32_16x16x32_bf16 v[90:93], v[6:9], v[62:65], v[90:93]
	v_mfma_f32_16x16x32_bf16 v[94:97], v[14:17], v[62:65], v[94:97]
	v_mfma_f32_16x16x32_bf16 v[98:101], v[18:21], v[34:37], 0
	v_mfma_f32_16x16x32_bf16 v[34:37], v[26:29], v[34:37], 0
	v_mfma_f32_16x16x32_bf16 v[98:101], v[22:25], v[38:41], v[98:101]
	v_mfma_f32_16x16x32_bf16 v[34:37], v[30:33], v[38:41], v[34:37]
	v_mfma_f32_16x16x32_bf16 v[38:41], v[18:21], v[42:45], 0
	v_mfma_f32_16x16x32_bf16 v[42:45], v[26:29], v[42:45], 0
	v_mfma_f32_16x16x32_bf16 v[38:41], v[22:25], v[46:49], v[38:41]
	v_mfma_f32_16x16x32_bf16 v[42:45], v[30:33], v[46:49], v[42:45]
	v_mfma_f32_16x16x32_bf16 v[46:49], v[18:21], v[50:53], 0
	v_mfma_f32_16x16x32_bf16 v[50:53], v[26:29], v[50:53], 0
	v_mfma_f32_16x16x32_bf16 v[46:49], v[22:25], v[54:57], v[46:49]
	v_mfma_f32_16x16x32_bf16 v[50:53], v[30:33], v[54:57], v[50:53]
	v_mfma_f32_16x16x32_bf16 v[54:57], v[18:21], v[58:61], 0
	v_mfma_f32_16x16x32_bf16 v[58:61], v[26:29], v[58:61], 0
	v_mfma_f32_16x16x32_bf16 v[54:57], v[22:25], v[62:65], v[54:57]
	v_mfma_f32_16x16x32_bf16 v[58:61], v[30:33], v[62:65], v[58:61]
	s_setprio 0
	s_barrier
	s_add_i32 s75, s72, s7
	v_lshl_add_u64 v[188:189], s[44:45], 0, v[148:149]
	s_add_i32 s31, s75, 0x2000
	v_lshl_add_u64 v[130:131], v[188:189], 0, s[26:27]
	s_mov_b32 m0, s75
	v_lshl_add_u64 v[218:219], s[44:45], 0, v[152:153]
	s_add_u32 s78, s44, 0x10100
	ds_read_b128 v[62:65], v192 offset:16384
	ds_read_b128 v[102:105], v192 offset:17408
	ds_read_b128 v[106:109], v192 offset:18432
	ds_read_b128 v[110:113], v192 offset:19456
	ds_read_b128 v[114:117], v192 offset:20480
	ds_read_b128 v[118:121], v192 offset:21504
	ds_read_b128 v[122:125], v192 offset:22528
	ds_read_b128 v[126:129], v192 offset:23552
	global_load_lds_dwordx4 v[130:131], off
	v_lshl_add_u64 v[130:131], v[218:219], 0, s[26:27]
	s_mov_b32 m0, s31
	s_addc_u32 s79, s45, 0
	s_add_i32 s35, s73, s7
	global_load_lds_dwordx4 v[130:131], off
	v_lshl_add_u64 v[130:131], s[78:79], 0, v[148:149]
	s_mov_b32 m0, s35
	s_add_i32 s74, s35, 0x2000
	global_load_lds_dwordx4 v[130:131], off
	v_lshl_add_u64 v[130:131], s[78:79], 0, v[152:153]
	s_mov_b32 m0, s74
	v_lshl_add_u64 v[220:221], s[40:41], 0, v[146:147]
	global_load_lds_dwordx4 v[130:131], off
	v_lshl_add_u64 v[130:131], v[220:221], 0, s[26:27]
	s_mov_b32 m0, s43
	v_lshl_add_u64 v[222:223], s[40:41], 0, v[150:151]
	global_load_lds_dwordx4 v[130:131], off
	v_lshl_add_u64 v[130:131], v[222:223], 0, s[26:27]
	s_mov_b32 m0, s50
	s_nop 0
	global_load_lds_dwordx4 v[130:131], off
	s_waitcnt vmcnt(8)
	s_waitcnt lgkmcnt(0)
	s_barrier
	s_setprio 1
	v_mfma_f32_16x16x32_bf16 v[130:133], v[2:5], v[62:65], 0
	v_mfma_f32_16x16x32_bf16 v[138:141], v[2:5], v[106:109], 0
	v_mfma_f32_16x16x32_bf16 v[158:161], v[2:5], v[114:117], 0
	v_mfma_f32_16x16x32_bf16 v[2:5], v[2:5], v[122:125], 0
	v_mfma_f32_16x16x32_bf16 v[130:133], v[6:9], v[102:105], v[130:133]
	v_mfma_f32_16x16x32_bf16 v[134:137], v[10:13], v[62:65], 0
	v_mfma_f32_16x16x32_bf16 v[138:141], v[6:9], v[110:113], v[138:141]
	v_mfma_f32_16x16x32_bf16 v[142:145], v[10:13], v[106:109], 0
	v_mfma_f32_16x16x32_bf16 v[158:161], v[6:9], v[118:121], v[158:161]
	v_mfma_f32_16x16x32_bf16 v[2:5], v[6:9], v[126:129], v[2:5]
	v_mfma_f32_16x16x32_bf16 v[6:9], v[10:13], v[122:125], 0
	v_mfma_f32_16x16x32_bf16 v[134:137], v[14:17], v[102:105], v[134:137]
	v_mfma_f32_16x16x32_bf16 v[142:145], v[14:17], v[110:113], v[142:145]
	v_mfma_f32_16x16x32_bf16 v[162:165], v[10:13], v[114:117], 0
	v_mfma_f32_16x16x32_bf16 v[6:9], v[14:17], v[126:129], v[6:9]
	v_mfma_f32_16x16x32_bf16 v[162:165], v[14:17], v[118:121], v[162:165]
	v_mfma_f32_16x16x32_bf16 v[10:13], v[18:21], v[62:65], 0
	v_mfma_f32_16x16x32_bf16 v[14:17], v[26:29], v[62:65], 0
	v_mfma_f32_16x16x32_bf16 v[10:13], v[22:25], v[102:105], v[10:13]
	v_mfma_f32_16x16x32_bf16 v[14:17], v[30:33], v[102:105], v[14:17]
	v_mfma_f32_16x16x32_bf16 v[62:65], v[18:21], v[106:109], 0
	v_mfma_f32_16x16x32_bf16 v[102:105], v[26:29], v[106:109], 0
	v_mfma_f32_16x16x32_bf16 v[62:65], v[22:25], v[110:113], v[62:65]
	v_mfma_f32_16x16x32_bf16 v[102:105], v[30:33], v[110:113], v[102:105]
	v_mfma_f32_16x16x32_bf16 v[106:109], v[18:21], v[114:117], 0
	v_mfma_f32_16x16x32_bf16 v[110:113], v[26:29], v[114:117], 0
	v_mfma_f32_16x16x32_bf16 v[18:21], v[18:21], v[122:125], 0
	v_mfma_f32_16x16x32_bf16 v[106:109], v[22:25], v[118:121], v[106:109]
	v_mfma_f32_16x16x32_bf16 v[110:113], v[30:33], v[118:121], v[110:113]
	v_mfma_f32_16x16x32_bf16 v[18:21], v[22:25], v[126:129], v[18:21]
	v_mfma_f32_16x16x32_bf16 v[22:25], v[26:29], v[122:125], 0
	v_mfma_f32_16x16x32_bf16 v[22:25], v[30:33], v[126:129], v[22:25]
	s_setprio 0
	s_barrier
	s_add_i32 s76, 0, 0x18000
	s_add_i32 s84, 0, 0x1c000
	v_add_u32_e32 v234, s76, v173
	v_add_u32_e32 v235, s84, v173
	ds_read_b128 v[26:29], v234
	ds_read_b128 v[30:33], v234 offset:1024
	ds_read_b128 v[114:117], v234 offset:2048
	ds_read_b128 v[118:121], v234 offset:3072
	ds_read_b128 v[122:125], v235
	ds_read_b128 v[126:129], v235 offset:1024
	ds_read_b128 v[166:169], v235 offset:2048
	ds_read_b128 v[176:179], v235 offset:3072
	s_add_u32 s78, s40, 0x40100
	s_addc_u32 s79, s41, 0
	s_mov_b32 m0, s51
	v_lshl_add_u64 v[224:225], s[78:79], 0, v[146:147]
	ds_read_b128 v[180:183], v192 offset:32768
	ds_read_b128 v[184:187], v192 offset:33792
	ds_read_b128 v[194:197], v192 offset:34816
	ds_read_b128 v[198:201], v192 offset:35840
	ds_read_b128 v[202:205], v192 offset:36864
	ds_read_b128 v[206:209], v192 offset:37888
	ds_read_b128 v[210:213], v192 offset:38912
	ds_read_b128 v[214:217], v192 offset:39936
	global_load_lds_dwordx4 v[224:225], off
	v_lshl_add_u64 v[224:225], s[78:79], 0, v[150:151]
	s_mov_b32 m0, s54
	s_nop 0
	global_load_lds_dwordx4 v[224:225], off
	s_waitcnt vmcnt(8)
	s_waitcnt lgkmcnt(0)
	s_barrier
	s_setprio 1
	v_mfma_f32_16x16x32_bf16 v[66:69], v[26:29], v[180:183], v[66:69]
	v_mfma_f32_16x16x32_bf16 v[70:73], v[114:117], v[180:183], v[70:73]
	v_mfma_f32_16x16x32_bf16 v[74:77], v[26:29], v[194:197], v[74:77]
	v_mfma_f32_16x16x32_bf16 v[78:81], v[114:117], v[194:197], v[78:81]
	v_mfma_f32_16x16x32_bf16 v[82:85], v[26:29], v[202:205], v[82:85]
	v_mfma_f32_16x16x32_bf16 v[86:89], v[114:117], v[202:205], v[86:89]
	v_mfma_f32_16x16x32_bf16 v[90:93], v[26:29], v[210:213], v[90:93]
	v_mfma_f32_16x16x32_bf16 v[94:97], v[114:117], v[210:213], v[94:97]
	v_mfma_f32_16x16x32_bf16 v[66:69], v[30:33], v[184:187], v[66:69]
	v_mfma_f32_16x16x32_bf16 v[70:73], v[118:121], v[184:187], v[70:73]
	v_mfma_f32_16x16x32_bf16 v[74:77], v[30:33], v[198:201], v[74:77]
	v_mfma_f32_16x16x32_bf16 v[78:81], v[118:121], v[198:201], v[78:81]
	v_mfma_f32_16x16x32_bf16 v[82:85], v[30:33], v[206:209], v[82:85]
	v_mfma_f32_16x16x32_bf16 v[86:89], v[118:121], v[206:209], v[86:89]
	v_mfma_f32_16x16x32_bf16 v[90:93], v[30:33], v[214:217], v[90:93]
	v_mfma_f32_16x16x32_bf16 v[94:97], v[118:121], v[214:217], v[94:97]
	v_mfma_f32_16x16x32_bf16 v[98:101], v[122:125], v[180:183], v[98:101]
	v_mfma_f32_16x16x32_bf16 v[34:37], v[166:169], v[180:183], v[34:37]
	v_mfma_f32_16x16x32_bf16 v[38:41], v[122:125], v[194:197], v[38:41]
	v_mfma_f32_16x16x32_bf16 v[42:45], v[166:169], v[194:197], v[42:45]
	v_mfma_f32_16x16x32_bf16 v[46:49], v[122:125], v[202:205], v[46:49]
	v_mfma_f32_16x16x32_bf16 v[50:53], v[166:169], v[202:205], v[50:53]
	v_mfma_f32_16x16x32_bf16 v[54:57], v[122:125], v[210:213], v[54:57]
	v_mfma_f32_16x16x32_bf16 v[58:61], v[166:169], v[210:213], v[58:61]
	v_mfma_f32_16x16x32_bf16 v[98:101], v[126:129], v[184:187], v[98:101]
	v_mfma_f32_16x16x32_bf16 v[34:37], v[176:179], v[184:187], v[34:37]
	v_mfma_f32_16x16x32_bf16 v[38:41], v[126:129], v[198:201], v[38:41]
	v_mfma_f32_16x16x32_bf16 v[42:45], v[176:179], v[198:201], v[42:45]
	v_mfma_f32_16x16x32_bf16 v[46:49], v[126:129], v[206:209], v[46:49]
	v_mfma_f32_16x16x32_bf16 v[50:53], v[176:179], v[206:209], v[50:53]
	v_mfma_f32_16x16x32_bf16 v[54:57], v[126:129], v[214:217], v[54:57]
	v_mfma_f32_16x16x32_bf16 v[58:61], v[176:179], v[214:217], v[58:61]
	s_setprio 0
	s_barrier
	s_add_i32 s78, s76, s7
	s_add_i32 s76, s78, 0x2000
	v_lshl_add_u64 v[188:189], v[188:189], 0, s[28:29]
	s_mov_b32 m0, s78
	s_add_u32 s80, s44, 0x10180
	ds_read_b128 v[180:183], v192 offset:49152
	ds_read_b128 v[184:187], v192 offset:50176
	ds_read_b128 v[194:197], v192 offset:51200
	ds_read_b128 v[198:201], v192 offset:52224
	ds_read_b128 v[202:205], v192 offset:53248
	ds_read_b128 v[206:209], v192 offset:54272
	ds_read_b128 v[210:213], v192 offset:55296
	ds_read_b128 v[214:217], v192 offset:56320
	global_load_lds_dwordx4 v[188:189], off
	v_lshl_add_u64 v[188:189], v[218:219], 0, s[28:29]
	s_mov_b32 m0, s76
	s_addc_u32 s81, s45, 0
	s_add_i32 s44, s84, s7
	global_load_lds_dwordx4 v[188:189], off
	v_lshl_add_u64 v[188:189], s[80:81], 0, v[148:149]
	s_mov_b32 m0, s44
	s_add_i32 s45, s44, 0x2000
	global_load_lds_dwordx4 v[188:189], off
	v_lshl_add_u64 v[188:189], s[80:81], 0, v[152:153]
	s_mov_b32 m0, s45
	s_nop 0
	global_load_lds_dwordx4 v[188:189], off
	v_lshl_add_u64 v[188:189], v[220:221], 0, s[28:29]
	s_mov_b32 m0, s65
	s_nop 0
	global_load_lds_dwordx4 v[188:189], off
	v_lshl_add_u64 v[188:189], v[222:223], 0, s[28:29]
	s_mov_b32 m0, s70
	s_nop 0
	global_load_lds_dwordx4 v[188:189], off
	s_waitcnt vmcnt(8)
	s_waitcnt lgkmcnt(0)
	s_barrier
	s_setprio 1
	v_mfma_f32_16x16x32_bf16 v[130:133], v[26:29], v[180:183], v[130:133]
	v_mfma_f32_16x16x32_bf16 v[134:137], v[114:117], v[180:183], v[134:137]
	v_mfma_f32_16x16x32_bf16 v[138:141], v[26:29], v[194:197], v[138:141]
	v_mfma_f32_16x16x32_bf16 v[142:145], v[114:117], v[194:197], v[142:145]
	v_mfma_f32_16x16x32_bf16 v[2:5], v[26:29], v[210:213], v[2:5]
	v_mfma_f32_16x16x32_bf16 v[6:9], v[114:117], v[210:213], v[6:9]
	v_mfma_f32_16x16x32_bf16 v[130:133], v[30:33], v[184:187], v[130:133]
	v_mfma_f32_16x16x32_bf16 v[134:137], v[118:121], v[184:187], v[134:137]
	v_mfma_f32_16x16x32_bf16 v[138:141], v[30:33], v[198:201], v[138:141]
	v_mfma_f32_16x16x32_bf16 v[142:145], v[118:121], v[198:201], v[142:145]
	v_mfma_f32_16x16x32_bf16 v[158:161], v[26:29], v[202:205], v[158:161]
	v_mfma_f32_16x16x32_bf16 v[162:165], v[114:117], v[202:205], v[162:165]
	v_mfma_f32_16x16x32_bf16 v[2:5], v[30:33], v[214:217], v[2:5]
	v_mfma_f32_16x16x32_bf16 v[6:9], v[118:121], v[214:217], v[6:9]
	v_mfma_f32_16x16x32_bf16 v[158:161], v[30:33], v[206:209], v[158:161]
	v_mfma_f32_16x16x32_bf16 v[162:165], v[118:121], v[206:209], v[162:165]
	v_mfma_f32_16x16x32_bf16 v[10:13], v[122:125], v[180:183], v[10:13]
	v_mfma_f32_16x16x32_bf16 v[14:17], v[166:169], v[180:183], v[14:17]
	v_mfma_f32_16x16x32_bf16 v[26:29], v[122:125], v[194:197], v[62:65]
	v_mfma_f32_16x16x32_bf16 v[30:33], v[166:169], v[194:197], v[102:105]
	v_mfma_f32_16x16x32_bf16 v[62:65], v[122:125], v[202:205], v[106:109]
	v_mfma_f32_16x16x32_bf16 v[102:105], v[166:169], v[202:205], v[110:113]
	v_mfma_f32_16x16x32_bf16 v[10:13], v[126:129], v[184:187], v[10:13]
	v_mfma_f32_16x16x32_bf16 v[14:17], v[176:179], v[184:187], v[14:17]
	v_mfma_f32_16x16x32_bf16 v[62:65], v[126:129], v[206:209], v[62:65]
	v_mfma_f32_16x16x32_bf16 v[102:105], v[176:179], v[206:209], v[102:105]
	v_mfma_f32_16x16x32_bf16 v[18:21], v[122:125], v[210:213], v[18:21]
	v_mfma_f32_16x16x32_bf16 v[22:25], v[166:169], v[210:213], v[22:25]
	v_mfma_f32_16x16x32_bf16 v[26:29], v[126:129], v[198:201], v[26:29]
	v_mfma_f32_16x16x32_bf16 v[30:33], v[176:179], v[198:201], v[30:33]
	v_mfma_f32_16x16x32_bf16 v[18:21], v[126:129], v[214:217], v[18:21]
	v_mfma_f32_16x16x32_bf16 v[22:25], v[176:179], v[214:217], v[22:25]
	s_setprio 0
	s_barrier
	ds_read_b128 v[106:109], v190
	ds_read_b128 v[110:113], v190 offset:1024
	ds_read_b128 v[114:117], v190 offset:2048
	ds_read_b128 v[118:121], v190 offset:3072
	ds_read_b128 v[122:125], v191
	ds_read_b128 v[126:129], v191 offset:1024
	ds_read_b128 v[166:169], v191 offset:2048
	ds_read_b128 v[176:179], v191 offset:3072
	s_add_u32 s40, s40, 0x40180
	s_addc_u32 s41, s41, 0
	s_mov_b32 m0, s77
	v_lshl_add_u64 v[188:189], s[40:41], 0, v[146:147]
	ds_read_b128 v[180:183], v192
	ds_read_b128 v[184:187], v192 offset:1024
	ds_read_b128 v[194:197], v192 offset:2048
	ds_read_b128 v[198:201], v192 offset:3072
	ds_read_b128 v[202:205], v192 offset:4096
	ds_read_b128 v[206:209], v192 offset:5120
	ds_read_b128 v[210:213], v192 offset:6144
	ds_read_b128 v[214:217], v192 offset:7168
	global_load_lds_dwordx4 v[188:189], off
	v_lshl_add_u64 v[188:189], s[40:41], 0, v[150:151]
	s_mov_b32 m0, s9
	s_nop 0
	global_load_lds_dwordx4 v[188:189], off
	s_waitcnt vmcnt(8)
	s_waitcnt lgkmcnt(0)
	s_barrier
	s_setprio 1
	v_mfma_f32_16x16x32_bf16 v[66:69], v[106:109], v[180:183], v[66:69]
	v_mfma_f32_16x16x32_bf16 v[70:73], v[114:117], v[180:183], v[70:73]
	v_mfma_f32_16x16x32_bf16 v[74:77], v[106:109], v[194:197], v[74:77]
	v_mfma_f32_16x16x32_bf16 v[78:81], v[114:117], v[194:197], v[78:81]
	v_mfma_f32_16x16x32_bf16 v[82:85], v[106:109], v[202:205], v[82:85]
	v_mfma_f32_16x16x32_bf16 v[86:89], v[114:117], v[202:205], v[86:89]
	v_mfma_f32_16x16x32_bf16 v[90:93], v[106:109], v[210:213], v[90:93]
	v_mfma_f32_16x16x32_bf16 v[94:97], v[114:117], v[210:213], v[94:97]
	v_mfma_f32_16x16x32_bf16 v[66:69], v[110:113], v[184:187], v[66:69]
	v_mfma_f32_16x16x32_bf16 v[70:73], v[118:121], v[184:187], v[70:73]
	v_mfma_f32_16x16x32_bf16 v[74:77], v[110:113], v[198:201], v[74:77]
	v_mfma_f32_16x16x32_bf16 v[78:81], v[118:121], v[198:201], v[78:81]
	v_mfma_f32_16x16x32_bf16 v[82:85], v[110:113], v[206:209], v[82:85]
	v_mfma_f32_16x16x32_bf16 v[86:89], v[118:121], v[206:209], v[86:89]
	v_mfma_f32_16x16x32_bf16 v[90:93], v[110:113], v[214:217], v[90:93]
	v_mfma_f32_16x16x32_bf16 v[94:97], v[118:121], v[214:217], v[94:97]
	v_mfma_f32_16x16x32_bf16 v[34:37], v[166:169], v[180:183], v[34:37]
	v_mfma_f32_16x16x32_bf16 v[38:41], v[122:125], v[194:197], v[38:41]
	v_mfma_f32_16x16x32_bf16 v[42:45], v[166:169], v[194:197], v[42:45]
	v_mfma_f32_16x16x32_bf16 v[46:49], v[122:125], v[202:205], v[46:49]
	v_mfma_f32_16x16x32_bf16 v[50:53], v[166:169], v[202:205], v[50:53]
	v_mfma_f32_16x16x32_bf16 v[54:57], v[122:125], v[210:213], v[54:57]
	v_mfma_f32_16x16x32_bf16 v[58:61], v[166:169], v[210:213], v[58:61]
	v_mfma_f32_16x16x32_bf16 v[98:101], v[122:125], v[180:183], v[98:101]
	v_mfma_f32_16x16x32_bf16 v[34:37], v[176:179], v[184:187], v[34:37]
	v_mfma_f32_16x16x32_bf16 v[38:41], v[126:129], v[198:201], v[38:41]
	v_mfma_f32_16x16x32_bf16 v[42:45], v[176:179], v[198:201], v[42:45]
	v_mfma_f32_16x16x32_bf16 v[46:49], v[126:129], v[206:209], v[46:49]
	v_mfma_f32_16x16x32_bf16 v[50:53], v[176:179], v[206:209], v[50:53]
	v_mfma_f32_16x16x32_bf16 v[54:57], v[126:129], v[214:217], v[54:57]
	v_mfma_f32_16x16x32_bf16 v[58:61], v[176:179], v[214:217], v[58:61]
	v_mfma_f32_16x16x32_bf16 v[218:221], v[126:129], v[184:187], v[98:101]
	s_setprio 0
	s_barrier
	s_mov_b32 m0, s75
	v_lshl_add_u64 v[188:189], s[46:47], 0, v[148:149]
	s_add_u32 s40, s46, 0x10000
	ds_read_b128 v[98:101], v192 offset:16384
	ds_read_b128 v[180:183], v192 offset:17408
	ds_read_b128 v[184:187], v192 offset:18432
	ds_read_b128 v[194:197], v192 offset:19456
	ds_read_b128 v[198:201], v192 offset:20480
	ds_read_b128 v[202:205], v192 offset:21504
	ds_read_b128 v[206:209], v192 offset:22528
	ds_read_b128 v[210:213], v192 offset:23552
	s_cmp_lg_u32 s33, 0x100
	s_cselect_b64 exec, -1, 0
	global_load_lds_dwordx4 v[188:189], off
	v_lshl_add_u64 v[154:155], s[46:47], 0, v[152:153]
	s_mov_b32 m0, s31
	s_addc_u32 s41, s47, 0
	global_load_lds_dwordx4 v[154:155], off
	v_lshl_add_u64 v[214:215], s[40:41], 0, v[148:149]
	s_mov_b32 m0, s35
	v_lshl_add_u64 v[0:1], s[48:49], 0, v[146:147]
	global_load_lds_dwordx4 v[214:215], off
	v_lshl_add_u64 v[214:215], s[40:41], 0, v[152:153]
	s_mov_b32 m0, s74
	v_lshl_add_u64 v[156:157], s[48:49], 0, v[150:151]
	global_load_lds_dwordx4 v[214:215], off
	s_mov_b32 m0, s43
	s_nop 0
	global_load_lds_dwordx4 v[0:1], off
	s_mov_b32 m0, s50
	s_nop 0
	global_load_lds_dwordx4 v[156:157], off
	s_mov_b64 exec, -1
	s_waitcnt vmcnt(8)
	s_waitcnt lgkmcnt(0)
	s_barrier
	s_setprio 1
	v_mfma_f32_16x16x32_bf16 v[130:133], v[106:109], v[98:101], v[130:133]
	v_mfma_f32_16x16x32_bf16 v[214:217], v[110:113], v[180:183], v[130:133]
	v_mfma_f32_16x16x32_bf16 v[130:133], v[114:117], v[98:101], v[134:137]
	v_mfma_f32_16x16x32_bf16 v[222:225], v[118:121], v[180:183], v[130:133]
	v_mfma_f32_16x16x32_bf16 v[130:133], v[106:109], v[184:187], v[138:141]
	v_mfma_f32_16x16x32_bf16 v[226:229], v[110:113], v[194:197], v[130:133]
	v_mfma_f32_16x16x32_bf16 v[130:133], v[114:117], v[184:187], v[142:145]
	v_mfma_f32_16x16x32_bf16 v[230:233], v[118:121], v[194:197], v[130:133]
	v_mfma_f32_16x16x32_bf16 v[130:133], v[106:109], v[198:201], v[158:161]
	v_mfma_f32_16x16x32_bf16 v[2:5], v[106:109], v[206:209], v[2:5]
	v_mfma_f32_16x16x32_bf16 v[6:9], v[114:117], v[206:209], v[6:9]
	v_mfma_f32_16x16x32_bf16 v[158:161], v[110:113], v[202:205], v[130:133]
	v_mfma_f32_16x16x32_bf16 v[130:133], v[114:117], v[198:201], v[162:165]
	v_mfma_f32_16x16x32_bf16 v[2:5], v[110:113], v[210:213], v[2:5]
	v_mfma_f32_16x16x32_bf16 v[6:9], v[118:121], v[210:213], v[6:9]
	v_mfma_f32_16x16x32_bf16 v[162:165], v[118:121], v[202:205], v[130:133]
	v_mfma_f32_16x16x32_bf16 v[10:13], v[122:125], v[98:101], v[10:13]
	v_mfma_f32_16x16x32_bf16 v[14:17], v[166:169], v[98:101], v[14:17]
	v_mfma_f32_16x16x32_bf16 v[62:65], v[122:125], v[198:201], v[62:65]
	v_mfma_f32_16x16x32_bf16 v[10:13], v[126:129], v[180:183], v[10:13]
	v_mfma_f32_16x16x32_bf16 v[14:17], v[176:179], v[180:183], v[14:17]
	v_mfma_f32_16x16x32_bf16 v[26:29], v[122:125], v[184:187], v[26:29]
	v_mfma_f32_16x16x32_bf16 v[30:33], v[166:169], v[184:187], v[30:33]
	v_mfma_f32_16x16x32_bf16 v[180:183], v[126:129], v[202:205], v[62:65]
	v_mfma_f32_16x16x32_bf16 v[62:65], v[166:169], v[198:201], v[102:105]
	v_mfma_f32_16x16x32_bf16 v[18:21], v[122:125], v[206:209], v[18:21]
	v_mfma_f32_16x16x32_bf16 v[22:25], v[166:169], v[206:209], v[22:25]
	v_mfma_f32_16x16x32_bf16 v[26:29], v[126:129], v[194:197], v[26:29]
	v_mfma_f32_16x16x32_bf16 v[30:33], v[176:179], v[194:197], v[30:33]
	v_mfma_f32_16x16x32_bf16 v[184:187], v[176:179], v[202:205], v[62:65]
	v_mfma_f32_16x16x32_bf16 v[18:21], v[126:129], v[210:213], v[18:21]
	v_mfma_f32_16x16x32_bf16 v[22:25], v[176:179], v[210:213], v[22:25]
	s_setprio 0
	s_barrier
	ds_read_b128 v[62:65], v234
	ds_read_b128 v[166:169], v234 offset:1024
	ds_read_b128 v[176:179], v234 offset:2048
	ds_read_b128 v[194:197], v234 offset:3072
	ds_read_b128 v[198:201], v235
	ds_read_b128 v[202:205], v235 offset:1024
	ds_read_b128 v[206:209], v235 offset:2048
	ds_read_b128 v[210:213], v235 offset:3072
	s_add_u32 s40, s48, 0x40000
	s_addc_u32 s41, s49, 0
	s_mov_b32 m0, s51
	v_lshl_add_u64 v[98:99], s[40:41], 0, v[146:147]
	ds_read_b128 v[106:109], v192 offset:32768
	ds_read_b128 v[110:113], v192 offset:33792
	ds_read_b128 v[126:129], v192 offset:34816
	ds_read_b128 v[234:237], v192 offset:35840
	ds_read_b128 v[238:241], v192 offset:36864
	ds_read_b128 v[242:245], v192 offset:37888
	ds_read_b128 v[246:249], v192 offset:38912
	ds_read_b128 v[250:253], v192 offset:39936
	s_cmp_lg_u32 s33, 0x100
	s_cselect_b64 exec, -1, 0
	global_load_lds_dwordx4 v[98:99], off
	v_lshl_add_u64 v[98:99], s[40:41], 0, v[150:151]
	s_mov_b32 m0, s54
	s_nop 0
	global_load_lds_dwordx4 v[98:99], off
	s_mov_b64 exec, -1
	s_waitcnt vmcnt(8)
	s_waitcnt lgkmcnt(0)
	s_barrier
	s_setprio 1
	v_mfma_f32_16x16x32_bf16 v[66:69], v[62:65], v[106:109], v[66:69]
	v_mfma_f32_16x16x32_bf16 v[130:133], v[166:169], v[110:113], v[66:69]
	v_mfma_f32_16x16x32_bf16 v[66:69], v[176:179], v[106:109], v[70:73]
	v_mfma_f32_16x16x32_bf16 v[134:137], v[194:197], v[110:113], v[66:69]
	v_mfma_f32_16x16x32_bf16 v[66:69], v[62:65], v[126:129], v[74:77]
	v_mfma_f32_16x16x32_bf16 v[114:117], v[166:169], v[234:237], v[66:69]
	v_mfma_f32_16x16x32_bf16 v[66:69], v[176:179], v[126:129], v[78:81]
	v_mfma_f32_16x16x32_bf16 v[118:121], v[194:197], v[234:237], v[66:69]
	v_mfma_f32_16x16x32_bf16 v[66:69], v[62:65], v[238:241], v[82:85]
	v_mfma_f32_16x16x32_bf16 v[98:101], v[166:169], v[242:245], v[66:69]
	v_mfma_f32_16x16x32_bf16 v[66:69], v[176:179], v[238:241], v[86:89]
	v_mfma_f32_16x16x32_bf16 v[102:105], v[194:197], v[242:245], v[66:69]
	v_mfma_f32_16x16x32_bf16 v[66:69], v[62:65], v[246:249], v[90:93]
	v_mfma_f32_16x16x32_bf16 v[82:85], v[166:169], v[250:253], v[66:69]
	v_mfma_f32_16x16x32_bf16 v[66:69], v[176:179], v[246:249], v[94:97]
	v_mfma_f32_16x16x32_bf16 v[86:89], v[194:197], v[250:253], v[66:69]
	v_mfma_f32_16x16x32_bf16 v[34:37], v[206:209], v[106:109], v[34:37]
	v_mfma_f32_16x16x32_bf16 v[142:145], v[210:213], v[110:113], v[34:37]
	v_mfma_f32_16x16x32_bf16 v[34:37], v[198:201], v[126:129], v[38:41]
	v_mfma_f32_16x16x32_bf16 v[122:125], v[202:205], v[234:237], v[34:37]
	v_mfma_f32_16x16x32_bf16 v[34:37], v[206:209], v[126:129], v[42:45]
	v_mfma_f32_16x16x32_bf16 v[126:129], v[210:213], v[234:237], v[34:37]
	v_mfma_f32_16x16x32_bf16 v[34:37], v[198:201], v[238:241], v[46:49]
	v_mfma_f32_16x16x32_bf16 v[66:69], v[198:201], v[106:109], v[218:221]
	v_mfma_f32_16x16x32_bf16 v[106:109], v[202:205], v[242:245], v[34:37]
	v_mfma_f32_16x16x32_bf16 v[34:37], v[206:209], v[238:241], v[50:53]
	v_mfma_f32_16x16x32_bf16 v[138:141], v[202:205], v[110:113], v[66:69]
	v_mfma_f32_16x16x32_bf16 v[110:113], v[210:213], v[242:245], v[34:37]
	v_mfma_f32_16x16x32_bf16 v[34:37], v[198:201], v[246:249], v[54:57]
	v_mfma_f32_16x16x32_bf16 v[90:93], v[202:205], v[250:253], v[34:37]
	v_mfma_f32_16x16x32_bf16 v[34:37], v[206:209], v[246:249], v[58:61]
	v_mfma_f32_16x16x32_bf16 v[94:97], v[210:213], v[250:253], v[34:37]
	s_setprio 0
	s_barrier
	s_mov_b32 m0, s78
	s_nop 3
	v_lshl_add_u64 v[34:35], v[188:189], 0, s[18:19]
	s_add_u32 s40, s46, 0x10080
	ds_read_b128 v[42:45], v192 offset:49152
	ds_read_b128 v[46:49], v192 offset:50176
	ds_read_b128 v[218:221], v192 offset:51200
	ds_read_b128 v[234:237], v192 offset:52224
	ds_read_b128 v[238:241], v192 offset:53248
	ds_read_b128 v[242:245], v192 offset:54272
	ds_read_b128 v[246:249], v192 offset:55296
	ds_read_b128 v[250:253], v192 offset:56320
	s_cmp_lg_u32 s33, 0x100
	s_cselect_b64 exec, -1, 0
	global_load_lds_dwordx4 v[34:35], off
	v_lshl_add_u64 v[34:35], v[154:155], 0, s[18:19]
	s_mov_b32 m0, s76
	s_addc_u32 s41, s47, 0
	global_load_lds_dwordx4 v[34:35], off
	v_lshl_add_u64 v[34:35], s[40:41], 0, v[148:149]
	s_mov_b32 m0, s44
	v_lshl_add_u64 v[0:1], v[0:1], 0, s[18:19]
	global_load_lds_dwordx4 v[34:35], off
	v_lshl_add_u64 v[34:35], s[40:41], 0, v[152:153]
	s_mov_b32 m0, s45
	s_nop 0
	global_load_lds_dwordx4 v[34:35], off
	s_mov_b32 m0, s65
	s_nop 0
	global_load_lds_dwordx4 v[0:1], off
	v_lshl_add_u64 v[0:1], v[156:157], 0, s[18:19]
	s_mov_b32 m0, s70
	s_nop 0
	global_load_lds_dwordx4 v[0:1], off
	s_mov_b64 exec, -1
	s_waitcnt vmcnt(8)
	s_waitcnt lgkmcnt(0)
	s_barrier
	s_setprio 1
	v_mfma_f32_16x16x32_bf16 v[34:37], v[62:65], v[42:45], v[214:217]
	v_mfma_f32_16x16x32_bf16 v[66:69], v[166:169], v[46:49], v[34:37]
	v_mfma_f32_16x16x32_bf16 v[34:37], v[176:179], v[42:45], v[222:225]
	v_mfma_f32_16x16x32_bf16 v[70:73], v[194:197], v[46:49], v[34:37]
	v_mfma_f32_16x16x32_bf16 v[34:37], v[62:65], v[218:221], v[226:229]
	v_mfma_f32_16x16x32_bf16 v[50:53], v[166:169], v[234:237], v[34:37]
	v_mfma_f32_16x16x32_bf16 v[34:37], v[176:179], v[218:221], v[230:233]
	v_mfma_f32_16x16x32_bf16 v[54:57], v[194:197], v[234:237], v[34:37]
	v_mfma_f32_16x16x32_bf16 v[34:37], v[62:65], v[238:241], v[158:161]
	v_mfma_f32_16x16x32_bf16 v[38:41], v[176:179], v[238:241], v[162:165]
	v_mfma_f32_16x16x32_bf16 v[2:5], v[62:65], v[246:249], v[2:5]
	v_mfma_f32_16x16x32_bf16 v[6:9], v[176:179], v[246:249], v[6:9]
	v_mfma_f32_16x16x32_bf16 v[34:37], v[166:169], v[242:245], v[34:37]
	v_mfma_f32_16x16x32_bf16 v[38:41], v[194:197], v[242:245], v[38:41]
	v_mfma_f32_16x16x32_bf16 v[2:5], v[166:169], v[250:253], v[2:5]
	v_mfma_f32_16x16x32_bf16 v[6:9], v[194:197], v[250:253], v[6:9]
	v_mfma_f32_16x16x32_bf16 v[10:13], v[198:201], v[42:45], v[10:13]
	v_mfma_f32_16x16x32_bf16 v[74:77], v[202:205], v[46:49], v[10:13]
	v_mfma_f32_16x16x32_bf16 v[10:13], v[206:209], v[42:45], v[14:17]
	v_mfma_f32_16x16x32_bf16 v[78:81], v[210:213], v[46:49], v[10:13]
	v_mfma_f32_16x16x32_bf16 v[10:13], v[198:201], v[218:221], v[26:29]
	v_mfma_f32_16x16x32_bf16 v[58:61], v[202:205], v[234:237], v[10:13]
	v_mfma_f32_16x16x32_bf16 v[10:13], v[206:209], v[218:221], v[30:33]
	v_mfma_f32_16x16x32_bf16 v[62:65], v[210:213], v[234:237], v[10:13]
	v_mfma_f32_16x16x32_bf16 v[10:13], v[198:201], v[238:241], v[180:183]
	v_mfma_f32_16x16x32_bf16 v[42:45], v[202:205], v[242:245], v[10:13]
	v_mfma_f32_16x16x32_bf16 v[10:13], v[206:209], v[238:241], v[184:187]
	v_mfma_f32_16x16x32_bf16 v[46:49], v[210:213], v[242:245], v[10:13]
	v_mfma_f32_16x16x32_bf16 v[10:13], v[198:201], v[246:249], v[18:21]
	v_mfma_f32_16x16x32_bf16 v[14:17], v[206:209], v[246:249], v[22:25]
	v_mfma_f32_16x16x32_bf16 v[10:13], v[202:205], v[250:253], v[10:13]
	v_mfma_f32_16x16x32_bf16 v[14:17], v[210:213], v[250:253], v[14:17]
	s_setprio 0
	s_barrier
	s_andn2_b64 vcc, exec, s[20:21]
	s_cbranch_vccnz .LBB0_1205
	s_barrier

.LBB0_1463:
	ds_read_b128 v[128:131], v169
	ds_read_b128 v[132:135], v169 offset:1024
	ds_read_b128 v[136:139], v169 offset:2048
	ds_read_b128 v[140:143], v169 offset:3072
	ds_read_b128 v[160:163], v170
	ds_read_b128 v[172:175], v170 offset:1024
	ds_read_b128 v[176:179], v170 offset:2048
	ds_read_b128 v[180:183], v170 offset:3072
	s_add_u32 s18, s16, 0xfff50080
	s_addc_u32 s19, s17, -1
	s_cmp_eq_u32 s45, 40
	s_cselect_b32 s21, s5, s19
	s_cselect_b32 s20, s4, s18
	s_cselect_b32 s19, s15, s44
	s_cselect_b32 s18, s14, s43
	s_add_i32 m0, s26, 0xc000
	ds_read_b128 v[184:187], v171
	ds_read_b128 v[188:191], v171 offset:1024
	ds_read_b128 v[192:195], v171 offset:2048
	ds_read_b128 v[196:199], v171 offset:3072
	ds_read_b128 v[200:203], v171 offset:4096
	ds_read_b128 v[204:207], v171 offset:5120
	ds_read_b128 v[208:211], v171 offset:6144
	ds_read_b128 v[212:215], v171 offset:7168
	global_load_lds_dwordx4 v152, s[16:17]
	s_add_i32 m0, s26, 0xe000
	s_nop 0
	global_load_lds_dwordx4 v154, s[16:17]
	s_waitcnt vmcnt(8)
	s_waitcnt lgkmcnt(0)
	s_barrier
	s_setprio 1
	v_mfma_f32_16x16x32_bf16 v[124:127], v[128:131], v[184:187], v[124:127]
	v_mfma_f32_16x16x32_bf16 v[120:123], v[136:139], v[184:187], v[120:123]
	v_mfma_f32_16x16x32_bf16 v[116:119], v[128:131], v[192:195], v[116:119]
	v_mfma_f32_16x16x32_bf16 v[108:111], v[136:139], v[192:195], v[108:111]
	v_mfma_f32_16x16x32_bf16 v[92:95], v[128:131], v[200:203], v[92:95]
	v_mfma_f32_16x16x32_bf16 v[88:91], v[136:139], v[200:203], v[88:91]
	v_mfma_f32_16x16x32_bf16 v[84:87], v[128:131], v[208:211], v[84:87]
	v_mfma_f32_16x16x32_bf16 v[80:83], v[136:139], v[208:211], v[80:83]
	v_mfma_f32_16x16x32_bf16 v[124:127], v[132:135], v[188:191], v[124:127]
	v_mfma_f32_16x16x32_bf16 v[120:123], v[140:143], v[188:191], v[120:123]
	v_mfma_f32_16x16x32_bf16 v[116:119], v[132:135], v[196:199], v[116:119]
	v_mfma_f32_16x16x32_bf16 v[108:111], v[140:143], v[196:199], v[108:111]
	v_mfma_f32_16x16x32_bf16 v[92:95], v[132:135], v[204:207], v[92:95]
	v_mfma_f32_16x16x32_bf16 v[88:91], v[140:143], v[204:207], v[88:91]
	v_mfma_f32_16x16x32_bf16 v[84:87], v[132:135], v[212:215], v[84:87]
	v_mfma_f32_16x16x32_bf16 v[80:83], v[140:143], v[212:215], v[80:83]
	v_mfma_f32_16x16x32_bf16 v[112:115], v[160:163], v[184:187], v[112:115]
	v_mfma_f32_16x16x32_bf16 v[104:107], v[176:179], v[184:187], v[104:107]
	v_mfma_f32_16x16x32_bf16 v[100:103], v[160:163], v[192:195], v[100:103]
	v_mfma_f32_16x16x32_bf16 v[96:99], v[176:179], v[192:195], v[96:99]
	v_mfma_f32_16x16x32_bf16 v[76:79], v[160:163], v[200:203], v[76:79]
	v_mfma_f32_16x16x32_bf16 v[72:75], v[176:179], v[200:203], v[72:75]
	v_mfma_f32_16x16x32_bf16 v[68:71], v[160:163], v[208:211], v[68:71]
	v_mfma_f32_16x16x32_bf16 v[64:67], v[176:179], v[208:211], v[64:67]
	v_mfma_f32_16x16x32_bf16 v[112:115], v[172:175], v[188:191], v[112:115]
	v_mfma_f32_16x16x32_bf16 v[104:107], v[180:183], v[188:191], v[104:107]
	v_mfma_f32_16x16x32_bf16 v[100:103], v[172:175], v[196:199], v[100:103]
	v_mfma_f32_16x16x32_bf16 v[96:99], v[180:183], v[196:199], v[96:99]
	v_mfma_f32_16x16x32_bf16 v[76:79], v[172:175], v[204:207], v[76:79]
	v_mfma_f32_16x16x32_bf16 v[72:75], v[180:183], v[204:207], v[72:75]
	v_mfma_f32_16x16x32_bf16 v[68:71], v[172:175], v[212:215], v[68:71]
	v_mfma_f32_16x16x32_bf16 v[64:67], v[180:183], v[212:215], v[64:67]
	s_setprio 0
	s_barrier
	s_add_u32 s98, s18, 0x80
	s_addc_u32 s99, s19, 0
	s_add_u32 s100, s20, 0x80
	s_addc_u32 s101, s21, 0
	s_add_i32 s46, s37, s25
	s_mov_b32 m0, s46
	ds_read_b128 v[184:187], v171 offset:16384
	ds_read_b128 v[188:191], v171 offset:17408
	ds_read_b128 v[192:195], v171 offset:18432
	ds_read_b128 v[196:199], v171 offset:19456
	ds_read_b128 v[200:203], v171 offset:20480
	ds_read_b128 v[204:207], v171 offset:21504
	ds_read_b128 v[208:211], v171 offset:22528
	ds_read_b128 v[212:215], v171 offset:23552
	s_cmp_eq_u32 s45, 40
	s_cselect_b64 exec, 0, -1
	s_cmp_lg_u32 s33, 0x100
	s_cselect_b64 exec, -1, exec
	global_load_lds_dwordx4 v146, s[18:19]
	s_add_i32 m0, s46, 0x2000
	s_add_u32 s46, s18, 0xb0000
	s_addc_u32 s47, s19, 0
	s_add_i32 s48, s38, s25
	global_load_lds_dwordx4 v150, s[18:19]
	s_mov_b32 m0, s48
	s_nop 0
	global_load_lds_dwordx4 v146, s[46:47]
	s_add_i32 m0, s48, 0x2000
	s_nop 0
	global_load_lds_dwordx4 v150, s[46:47]
	s_mov_b32 m0, s26
	s_nop 0
	global_load_lds_dwordx4 v144, s[20:21]
	s_mov_b32 m0, s27
	s_nop 0
	global_load_lds_dwordx4 v148, s[20:21]
	s_mov_b64 exec, -1
	s_waitcnt vmcnt(8)
	s_waitcnt lgkmcnt(0)
	s_barrier
	s_setprio 1
	v_mfma_f32_16x16x32_bf16 v[60:63], v[128:131], v[184:187], v[60:63]
	v_mfma_f32_16x16x32_bf16 v[56:59], v[136:139], v[184:187], v[56:59]
	v_mfma_f32_16x16x32_bf16 v[52:55], v[128:131], v[192:195], v[52:55]
	v_mfma_f32_16x16x32_bf16 v[48:51], v[136:139], v[192:195], v[48:51]
	v_mfma_f32_16x16x32_bf16 v[28:31], v[128:131], v[200:203], v[28:31]
	v_mfma_f32_16x16x32_bf16 v[24:27], v[136:139], v[200:203], v[24:27]
	v_mfma_f32_16x16x32_bf16 v[20:23], v[128:131], v[208:211], v[20:23]
	v_mfma_f32_16x16x32_bf16 v[16:19], v[136:139], v[208:211], v[16:19]
	v_mfma_f32_16x16x32_bf16 v[60:63], v[132:135], v[188:191], v[60:63]
	v_mfma_f32_16x16x32_bf16 v[56:59], v[140:143], v[188:191], v[56:59]
	v_mfma_f32_16x16x32_bf16 v[52:55], v[132:135], v[196:199], v[52:55]
	v_mfma_f32_16x16x32_bf16 v[48:51], v[140:143], v[196:199], v[48:51]
	v_mfma_f32_16x16x32_bf16 v[28:31], v[132:135], v[204:207], v[28:31]
	v_mfma_f32_16x16x32_bf16 v[24:27], v[140:143], v[204:207], v[24:27]
	v_mfma_f32_16x16x32_bf16 v[20:23], v[132:135], v[212:215], v[20:23]
	v_mfma_f32_16x16x32_bf16 v[16:19], v[140:143], v[212:215], v[16:19]
	v_mfma_f32_16x16x32_bf16 v[44:47], v[160:163], v[184:187], v[44:47]
	v_mfma_f32_16x16x32_bf16 v[40:43], v[176:179], v[184:187], v[40:43]
	v_mfma_f32_16x16x32_bf16 v[36:39], v[160:163], v[192:195], v[36:39]
	v_mfma_f32_16x16x32_bf16 v[32:35], v[176:179], v[192:195], v[32:35]
	v_mfma_f32_16x16x32_bf16 v[12:15], v[160:163], v[200:203], v[12:15]
	v_mfma_f32_16x16x32_bf16 v[8:11], v[176:179], v[200:203], v[8:11]
	v_mfma_f32_16x16x32_bf16 v[4:7], v[160:163], v[208:211], v[4:7]
	v_mfma_f32_16x16x32_bf16 v[0:3], v[176:179], v[208:211], v[0:3]
	v_mfma_f32_16x16x32_bf16 v[44:47], v[172:175], v[188:191], v[44:47]
	v_mfma_f32_16x16x32_bf16 v[40:43], v[180:183], v[188:191], v[40:43]
	v_mfma_f32_16x16x32_bf16 v[36:39], v[172:175], v[196:199], v[36:39]
	v_mfma_f32_16x16x32_bf16 v[32:35], v[180:183], v[196:199], v[32:35]
	v_mfma_f32_16x16x32_bf16 v[12:15], v[172:175], v[204:207], v[12:15]
	v_mfma_f32_16x16x32_bf16 v[8:11], v[180:183], v[204:207], v[8:11]
	v_mfma_f32_16x16x32_bf16 v[4:7], v[172:175], v[212:215], v[4:7]
	v_mfma_f32_16x16x32_bf16 v[0:3], v[180:183], v[212:215], v[0:3]
	s_setprio 0
	s_barrier
	s_add_i32 s46, 0, 0x18000
	s_add_i32 s47, 0, 0x1c000
	v_add_u32_e32 v140, s46, v167
	v_add_u32_e32 v180, s47, v167
	ds_read_b128 v[128:131], v140
	ds_read_b128 v[132:135], v140 offset:1024
	ds_read_b128 v[136:139], v140 offset:2048
	ds_read_b128 v[140:143], v140 offset:3072
	ds_read_b128 v[160:163], v180
	ds_read_b128 v[172:175], v180 offset:1024
	ds_read_b128 v[176:179], v180 offset:2048
	ds_read_b128 v[180:183], v180 offset:3072
	s_add_u32 s20, s20, 0xb0000
	s_addc_u32 s21, s21, 0
	s_mov_b32 m0, s28
	ds_read_b128 v[184:187], v171 offset:32768
	ds_read_b128 v[188:191], v171 offset:33792
	ds_read_b128 v[192:195], v171 offset:34816
	ds_read_b128 v[196:199], v171 offset:35840
	ds_read_b128 v[200:203], v171 offset:36864
	ds_read_b128 v[204:207], v171 offset:37888
	ds_read_b128 v[208:211], v171 offset:38912
	ds_read_b128 v[212:215], v171 offset:39936
	s_cmp_eq_u32 s45, 40
	s_cselect_b64 exec, 0, -1
	s_cmp_lg_u32 s33, 0x100
	s_cselect_b64 exec, -1, exec
	global_load_lds_dwordx4 v144, s[20:21]
	s_mov_b32 m0, s29
	s_nop 0
	global_load_lds_dwordx4 v148, s[20:21]
	s_mov_b64 exec, -1
	s_waitcnt vmcnt(8)
	s_waitcnt lgkmcnt(0)
	s_barrier
	s_setprio 1
	v_mfma_f32_16x16x32_bf16 v[124:127], v[128:131], v[184:187], v[124:127]
	v_mfma_f32_16x16x32_bf16 v[120:123], v[136:139], v[184:187], v[120:123]
	v_mfma_f32_16x16x32_bf16 v[116:119], v[128:131], v[192:195], v[116:119]
	v_mfma_f32_16x16x32_bf16 v[108:111], v[136:139], v[192:195], v[108:111]
	v_mfma_f32_16x16x32_bf16 v[92:95], v[128:131], v[200:203], v[92:95]
	v_mfma_f32_16x16x32_bf16 v[88:91], v[136:139], v[200:203], v[88:91]
	v_mfma_f32_16x16x32_bf16 v[84:87], v[128:131], v[208:211], v[84:87]
	v_mfma_f32_16x16x32_bf16 v[80:83], v[136:139], v[208:211], v[80:83]
	v_mfma_f32_16x16x32_bf16 v[124:127], v[132:135], v[188:191], v[124:127]
	v_mfma_f32_16x16x32_bf16 v[120:123], v[140:143], v[188:191], v[120:123]
	v_mfma_f32_16x16x32_bf16 v[116:119], v[132:135], v[196:199], v[116:119]
	v_mfma_f32_16x16x32_bf16 v[108:111], v[140:143], v[196:199], v[108:111]
	v_mfma_f32_16x16x32_bf16 v[92:95], v[132:135], v[204:207], v[92:95]
	v_mfma_f32_16x16x32_bf16 v[88:91], v[140:143], v[204:207], v[88:91]
	v_mfma_f32_16x16x32_bf16 v[84:87], v[132:135], v[212:215], v[84:87]
	v_mfma_f32_16x16x32_bf16 v[80:83], v[140:143], v[212:215], v[80:83]
	v_mfma_f32_16x16x32_bf16 v[112:115], v[160:163], v[184:187], v[112:115]
	v_mfma_f32_16x16x32_bf16 v[104:107], v[176:179], v[184:187], v[104:107]
	v_mfma_f32_16x16x32_bf16 v[100:103], v[160:163], v[192:195], v[100:103]
	v_mfma_f32_16x16x32_bf16 v[96:99], v[176:179], v[192:195], v[96:99]
	v_mfma_f32_16x16x32_bf16 v[76:79], v[160:163], v[200:203], v[76:79]
	v_mfma_f32_16x16x32_bf16 v[72:75], v[176:179], v[200:203], v[72:75]
	v_mfma_f32_16x16x32_bf16 v[68:71], v[160:163], v[208:211], v[68:71]
	v_mfma_f32_16x16x32_bf16 v[64:67], v[176:179], v[208:211], v[64:67]
	v_mfma_f32_16x16x32_bf16 v[112:115], v[172:175], v[188:191], v[112:115]
	v_mfma_f32_16x16x32_bf16 v[104:107], v[180:183], v[188:191], v[104:107]
	v_mfma_f32_16x16x32_bf16 v[100:103], v[172:175], v[196:199], v[100:103]
	v_mfma_f32_16x16x32_bf16 v[96:99], v[180:183], v[196:199], v[96:99]
	v_mfma_f32_16x16x32_bf16 v[76:79], v[172:175], v[204:207], v[76:79]
	v_mfma_f32_16x16x32_bf16 v[72:75], v[180:183], v[204:207], v[72:75]
	v_mfma_f32_16x16x32_bf16 v[68:71], v[172:175], v[212:215], v[68:71]
	v_mfma_f32_16x16x32_bf16 v[64:67], v[180:183], v[212:215], v[64:67]
	s_setprio 0
	s_barrier
	s_add_i32 s20, s46, s25
	s_mov_b32 m0, s20
	ds_read_b128 v[184:187], v171 offset:49152
	ds_read_b128 v[188:191], v171 offset:50176
	ds_read_b128 v[192:195], v171 offset:51200
	ds_read_b128 v[196:199], v171 offset:52224
	ds_read_b128 v[200:203], v171 offset:53248
	ds_read_b128 v[204:207], v171 offset:54272
	ds_read_b128 v[208:211], v171 offset:55296
	ds_read_b128 v[212:215], v171 offset:56320
	s_cmp_eq_u32 s45, 40
	s_cselect_b64 exec, 0, -1
	s_cmp_lg_u32 s33, 0x100
	s_cselect_b64 exec, -1, exec
	global_load_lds_dwordx4 v146, s[98:99]
	s_add_i32 m0, s20, 0x2000
	s_add_u32 s18, s18, 0xb0080
	s_addc_u32 s19, s19, 0
	s_add_i32 s20, s47, s25
	global_load_lds_dwordx4 v150, s[98:99]
	s_mov_b32 m0, s20
	s_nop 0
	global_load_lds_dwordx4 v146, s[18:19]
	s_add_i32 m0, s20, 0x2000
	s_nop 0
	global_load_lds_dwordx4 v150, s[18:19]
	s_mov_b32 m0, s35
	s_nop 0
	global_load_lds_dwordx4 v144, s[100:101]
	s_mov_b32 m0, s36
	s_nop 0
	global_load_lds_dwordx4 v148, s[100:101]
	s_mov_b64 exec, -1
	s_waitcnt vmcnt(8)
	s_waitcnt lgkmcnt(0)
	s_barrier
	s_setprio 1
	v_mfma_f32_16x16x32_bf16 v[60:63], v[128:131], v[184:187], v[60:63]
	v_mfma_f32_16x16x32_bf16 v[56:59], v[136:139], v[184:187], v[56:59]
	v_mfma_f32_16x16x32_bf16 v[52:55], v[128:131], v[192:195], v[52:55]
	v_mfma_f32_16x16x32_bf16 v[48:51], v[136:139], v[192:195], v[48:51]
	v_mfma_f32_16x16x32_bf16 v[28:31], v[128:131], v[200:203], v[28:31]
	v_mfma_f32_16x16x32_bf16 v[24:27], v[136:139], v[200:203], v[24:27]
	v_mfma_f32_16x16x32_bf16 v[20:23], v[128:131], v[208:211], v[20:23]
	v_mfma_f32_16x16x32_bf16 v[16:19], v[136:139], v[208:211], v[16:19]
	v_mfma_f32_16x16x32_bf16 v[60:63], v[132:135], v[188:191], v[60:63]
	v_mfma_f32_16x16x32_bf16 v[56:59], v[140:143], v[188:191], v[56:59]
	v_mfma_f32_16x16x32_bf16 v[52:55], v[132:135], v[196:199], v[52:55]
	v_mfma_f32_16x16x32_bf16 v[48:51], v[140:143], v[196:199], v[48:51]
	v_mfma_f32_16x16x32_bf16 v[28:31], v[132:135], v[204:207], v[28:31]
	v_mfma_f32_16x16x32_bf16 v[24:27], v[140:143], v[204:207], v[24:27]
	v_mfma_f32_16x16x32_bf16 v[20:23], v[132:135], v[212:215], v[20:23]
	v_mfma_f32_16x16x32_bf16 v[16:19], v[140:143], v[212:215], v[16:19]
	v_mfma_f32_16x16x32_bf16 v[44:47], v[160:163], v[184:187], v[44:47]
	v_mfma_f32_16x16x32_bf16 v[40:43], v[176:179], v[184:187], v[40:43]
	v_mfma_f32_16x16x32_bf16 v[36:39], v[160:163], v[192:195], v[36:39]
	v_mfma_f32_16x16x32_bf16 v[32:35], v[176:179], v[192:195], v[32:35]
	v_mfma_f32_16x16x32_bf16 v[12:15], v[160:163], v[200:203], v[12:15]
	v_mfma_f32_16x16x32_bf16 v[8:11], v[176:179], v[200:203], v[8:11]
	v_mfma_f32_16x16x32_bf16 v[4:7], v[160:163], v[208:211], v[4:7]
	v_mfma_f32_16x16x32_bf16 v[0:3], v[176:179], v[208:211], v[0:3]
	v_mfma_f32_16x16x32_bf16 v[44:47], v[172:175], v[188:191], v[44:47]
	v_mfma_f32_16x16x32_bf16 v[40:43], v[180:183], v[188:191], v[40:43]
	v_mfma_f32_16x16x32_bf16 v[36:39], v[172:175], v[196:199], v[36:39]
	v_mfma_f32_16x16x32_bf16 v[32:35], v[180:183], v[196:199], v[32:35]
	v_mfma_f32_16x16x32_bf16 v[12:15], v[172:175], v[204:207], v[12:15]
	v_mfma_f32_16x16x32_bf16 v[8:11], v[180:183], v[204:207], v[8:11]
	v_mfma_f32_16x16x32_bf16 v[4:7], v[172:175], v[212:215], v[4:7]
	v_mfma_f32_16x16x32_bf16 v[0:3], v[180:183], v[212:215], v[0:3]
	s_setprio 0
	s_barrier
	s_add_i32 s45, s45, 2
	s_add_u32 s16, s16, 0x100
	s_addc_u32 s17, s17, 0
	s_add_u32 s43, s43, 0x100
	s_addc_u32 s44, s44, 0
	s_cmp_gt_u32 s45, 41
	s_cbranch_scc0 .LBB0_1463
	s_and_b64 vcc, exec, s[12:13]
	s_cbranch_vccz .LBB0_1466
	s_barrier
